# attention ctx-key/value MFMA chains: LDS fragment reads software-pipelined 8 deep (were read-wait-mfma serialized)
# speedup vs baseline: 1.0061x; 1.0061x over previous
; template <bool LOCAL>
; __device__ __forceinline__ void attn_unit(const bf16_t* Q, const bf16_t* KT, const bf16_t* VT, bf16_t* O, LAS unsigned char* lds, int b, int h, int r, int w, int tq, int lane) {
;     ...
;     float mx = -INFINITY;
; #pragma unroll
;     for (int i = 0; i < 2 * NP; ++i) mx = fmaxf(mx, fmaxf(fmaxf(s[i][0], s[i][1]), fmaxf(s[i][2], s[i][3])));
;     mx = fmaxf(mx, __shfl_xor(mx, 16)); mx = fmaxf(mx, __shfl_xor(mx, 32));
.LBB9_673:
	s_or_b64 exec, exec, s[34:35]
	v_max_f32_e32 v66, v126, v126
	v_max_f32_e32 v67, v134, v134
	v_max_f32_e32 v66, v67, v66
	v_max_f32_e32 v67, v123, v123
	v_max_f32_e32 v68, v129, v129
	v_max_f32_e32 v67, v68, v67
	v_max3_f32 v66, v133, v132, v66
	v_max3_f32 v67, v128, v127, v67
	v_max3_f32 v66, v66, s16, v67
	v_max_f32_e32 v67, v118, v118
	v_max_f32_e32 v68, v125, v125
	v_max_f32_e32 v67, v68, v67
	v_max_f32_e32 v68, v115, v115
	v_max_f32_e32 v69, v121, v121
	v_max_f32_e32 v68, v69, v68
	v_max3_f32 v67, v124, v122, v67
	v_max3_f32 v68, v120, v119, v68
	v_max3_f32 v66, v66, v67, v68
	v_max_f32_e32 v67, v110, v110
	v_max_f32_e32 v68, v117, v117
	v_max_f32_e32 v67, v68, v67
	v_max_f32_e32 v68, v113, v113
	v_max_f32_e32 v69, v135, v135
	v_max_f32_e32 v68, v69, v68
	v_max3_f32 v67, v116, v114, v67
	v_max3_f32 v68, v112, v111, v68
	v_max3_f32 v66, v66, v67, v68
	v_max_f32_e32 v67, v102, v102
	v_max_f32_e32 v68, v109, v109
	v_max_f32_e32 v67, v68, v67
	v_max_f32_e32 v68, v99, v99
	v_max_f32_e32 v69, v105, v105
	v_max_f32_e32 v68, v69, v68
	v_max3_f32 v67, v108, v107, v67
	v_max3_f32 v68, v104, v103, v68
	v_max3_f32 v66, v66, v67, v68
	v_max_f32_e32 v67, v94, v94
	v_max_f32_e32 v68, v101, v101
	v_max_f32_e32 v67, v68, v67
	v_max_f32_e32 v68, v91, v91
	v_max_f32_e32 v69, v97, v97
	v_max_f32_e32 v68, v69, v68
	v_max3_f32 v67, v100, v98, v67
	v_max3_f32 v68, v96, v95, v68
	v_max3_f32 v66, v66, v67, v68
	v_max_f32_e32 v67, v86, v86
	v_max_f32_e32 v68, v93, v93
	v_max_f32_e32 v67, v68, v67
	v_max_f32_e32 v68, v89, v89
	v_max_f32_e32 v69, v138, v138
	v_max_f32_e32 v68, v69, v68
	v_max3_f32 v67, v92, v90, v67
	v_max3_f32 v68, v88, v87, v68
	v_max3_f32 v66, v66, v67, v68
	v_max_f32_e32 v67, v139, v139
	v_max_f32_e32 v68, v141, v141
	v_max_f32_e32 v67, v68, v67
	v_max_f32_e32 v68, v197, v197
	v_max_f32_e32 v69, v199, v199
	v_max_f32_e32 v68, v69, v68
	v_max3_f32 v67, v137, v136, v67
	v_max3_f32 v68, v195, v140, v68
	v_max3_f32 v66, v66, v67, v68
	v_max_f32_e32 v67, v200, v200
	v_max_f32_e32 v68, v202, v202
	v_max_f32_e32 v67, v68, v67
	v_max_f32_e32 v68, v204, v204
	v_max_f32_e32 v69, v205, v205
	v_max_f32_e32 v68, v69, v68
	v_max3_f32 v67, v198, v196, v67
	v_max3_f32 v68, v203, v201, v68
	v_max3_f32 v66, v66, v67, v68
	v_max_f32_e32 v67, v5, v5
	v_max_f32_e32 v68, v4, v4
	v_max_f32_e32 v67, v68, v67
	v_max_f32_e32 v68, v13, v13
	v_max_f32_e32 v69, v12, v12
	v_max_f32_e32 v68, v69, v68
	v_max3_f32 v67, v2, v3, v67
	v_max3_f32 v68, v10, v11, v68
	v_max3_f32 v66, v66, v67, v68
	v_max_f32_e32 v67, v9, v9
	v_max_f32_e32 v68, v8, v8
	v_max_f32_e32 v67, v68, v67
	v_max_f32_e32 v68, v21, v21
	v_max_f32_e32 v69, v20, v20
	v_max_f32_e32 v68, v69, v68
	v_max3_f32 v67, v6, v7, v67
	v_max3_f32 v68, v18, v19, v68
	v_max3_f32 v66, v66, v67, v68
	v_max_f32_e32 v67, v17, v17
	v_max_f32_e32 v68, v16, v16
	v_max_f32_e32 v67, v68, v67
	v_max_f32_e32 v68, v29, v29
	v_max_f32_e32 v69, v28, v28
	v_max_f32_e32 v68, v69, v68
	v_max3_f32 v67, v14, v15, v67
	v_max3_f32 v68, v26, v27, v68
	v_max3_f32 v66, v66, v67, v68
	v_max_f32_e32 v67, v25, v25
	v_max_f32_e32 v68, v24, v24
	v_max_f32_e32 v67, v68, v67
	v_max_f32_e32 v68, v37, v37
	v_max_f32_e32 v69, v36, v36
	v_max_f32_e32 v68, v69, v68
	v_max3_f32 v67, v22, v23, v67
	v_max3_f32 v68, v34, v35, v68
	v_max3_f32 v66, v66, v67, v68
	v_max_f32_e32 v67, v33, v33
	v_max_f32_e32 v68, v32, v32
	v_max_f32_e32 v67, v68, v67
	v_max_f32_e32 v68, v45, v45
	v_max_f32_e32 v69, v44, v44
	v_max_f32_e32 v68, v69, v68
	v_max3_f32 v67, v30, v31, v67
	v_max3_f32 v68, v42, v43, v68
	v_max3_f32 v66, v66, v67, v68
	v_max_f32_e32 v67, v41, v41
	v_max_f32_e32 v68, v40, v40
	v_max_f32_e32 v67, v68, v67
	v_max_f32_e32 v68, v53, v53
	v_max_f32_e32 v69, v52, v52
	v_max_f32_e32 v68, v69, v68
	v_max3_f32 v67, v38, v39, v67
	v_max3_f32 v68, v50, v51, v68
	v_max3_f32 v66, v66, v67, v68
	v_max_f32_e32 v67, v49, v49
	v_max_f32_e32 v68, v48, v48
	v_max_f32_e32 v67, v68, v67
	v_max_f32_e32 v68, v61, v61
	v_max_f32_e32 v69, v60, v60
	v_max_f32_e32 v68, v69, v68
	v_max3_f32 v67, v46, v47, v67
	v_max3_f32 v68, v58, v59, v68
	v_max3_f32 v66, v66, v67, v68
	v_max_f32_e32 v67, v57, v57
	v_max_f32_e32 v68, v56, v56
	v_max_f32_e32 v67, v68, v67
	v_max_f32_e32 v68, v65, v65
	v_max_f32_e32 v69, v64, v64
	v_max_f32_e32 v68, v69, v68
	v_max3_f32 v67, v54, v55, v67
	v_max3_f32 v68, v62, v63, v68
	v_max3_f32 v66, v66, v67, v68
	ds_bpermute_b32 v67, v181, v66
	v_lshlrev_b64 v[130:131], 11, v[162:163]
	s_waitcnt lgkmcnt(0)
	v_max_f32_e32 v67, v67, v67
	v_max_f32_e32 v66, v66, v67
	ds_bpermute_b32 v67, v182, v66
	s_waitcnt lgkmcnt(0)
; __device__ __forceinline__ unsigned cvt_pk_bf16(float lo, float hi) { unsigned r; asm volatile("v_cvt_pk_bf16_f32 %0, %1, %2" : "=v"(r) : "v"(lo), "v"(hi)); return r; }
; __device__ __forceinline__ float fast_exp2(float x) { return __builtin_amdgcn_exp2f(x); }
; template <bool LOCAL>
; __device__ __forceinline__ void attn_unit(const bf16_t* Q, const bf16_t* KT, const bf16_t* VT, bf16_t* O, LAS unsigned char* lds, int b, int h, int r, int w, int tq, int lane) {
;     ...
;     float sum = 0.f; const float mxl = mx * 1.4426950408889634f;
;     bf16x8 pb[NP];
; #pragma unroll
;     for (int p = 0; p < NP; ++p) { float e[8];
; #pragma unroll
;         for (int f = 0; f < 2; ++f)
; #pragma unroll
;             for (int j = 0; j < 4; ++j) { e[4 * f + j] = fast_exp2(fmaf(s[2 * p + f][j], 1.4426950408889634f, -mxl)); sum += e[4 * f + j]; }
;         u32x4 pw; pw.x = cvt_pk_bf16(e[0], e[1]); pw.y = cvt_pk_bf16(e[2], e[3]); pw.z = cvt_pk_bf16(e[4], e[5]); pw.w = cvt_pk_bf16(e[6], e[7]);
;         pb[p] = __builtin_bit_cast(bf16x8, pw); }
	v_max_f32_e32 v67, v67, v67
	v_max_f32_e32 v66, v66, v67
	v_mul_f32_e32 v106, 0xbfb8aa3b, v66
	v_fmamk_f32 v66, v133, 0x3fb8aa3b, v106
	v_exp_f32_e32 v66, v66
	v_fmamk_f32 v68, v132, 0x3fb8aa3b, v106
	v_exp_f32_e32 v68, v68
	v_fmamk_f32 v69, v134, 0x3fb8aa3b, v106
	v_exp_f32_e32 v69, v69
	v_fmamk_f32 v70, v126, 0x3fb8aa3b, v106
	v_exp_f32_e32 v70, v70
	v_fmamk_f32 v71, v128, 0x3fb8aa3b, v106
	v_add_f32_e32 v67, 0, v66
	v_exp_f32_e32 v71, v71
	v_fmamk_f32 v72, v127, 0x3fb8aa3b, v106
	v_add_f32_e32 v67, v68, v67
	v_exp_f32_e32 v72, v72
	v_fmamk_f32 v73, v129, 0x3fb8aa3b, v106
	v_add_f32_e32 v67, v69, v67
	v_exp_f32_e32 v73, v73
	v_fmamk_f32 v74, v123, 0x3fb8aa3b, v106
	v_add_f32_e32 v67, v70, v67
	v_exp_f32_e32 v74, v74
	v_add_f32_e32 v67, v71, v67
	v_add_f32_e32 v67, v72, v67
	v_add_f32_e32 v67, v73, v67
	v_add_f32_e32 v75, v74, v67
	v_cvt_pk_bf16_f32 v66, v66, v68
	v_cvt_pk_bf16_f32 v67, v69, v70
	v_fmamk_f32 v70, v124, 0x3fb8aa3b, v106
	v_exp_f32_e32 v70, v70
	v_cvt_pk_bf16_f32 v68, v71, v72
	v_fmamk_f32 v72, v122, 0x3fb8aa3b, v106
	v_cvt_pk_bf16_f32 v69, v73, v74
	v_exp_f32_e32 v72, v72
	v_fmamk_f32 v73, v125, 0x3fb8aa3b, v106
	v_exp_f32_e32 v73, v73
	v_fmamk_f32 v74, v118, 0x3fb8aa3b, v106
	v_add_f32_e32 v71, v70, v75
	v_exp_f32_e32 v74, v74
	v_fmamk_f32 v75, v120, 0x3fb8aa3b, v106
	v_exp_f32_e32 v75, v75
	v_fmamk_f32 v76, v119, 0x3fb8aa3b, v106
	v_add_f32_e32 v71, v72, v71
	v_exp_f32_e32 v76, v76
	v_fmamk_f32 v77, v121, 0x3fb8aa3b, v106
	v_add_f32_e32 v71, v73, v71
	v_exp_f32_e32 v77, v77
	v_fmamk_f32 v78, v115, 0x3fb8aa3b, v106
	v_add_f32_e32 v71, v74, v71
	v_exp_f32_e32 v78, v78
	v_add_f32_e32 v71, v75, v71
	v_add_f32_e32 v71, v76, v71
	v_add_f32_e32 v71, v77, v71
	v_add_f32_e32 v79, v78, v71
	v_cvt_pk_bf16_f32 v70, v70, v72
	v_cvt_pk_bf16_f32 v71, v73, v74
	v_fmamk_f32 v74, v116, 0x3fb8aa3b, v106
	v_exp_f32_e32 v74, v74
	v_cvt_pk_bf16_f32 v72, v75, v76
	v_fmamk_f32 v76, v114, 0x3fb8aa3b, v106
	v_cvt_pk_bf16_f32 v73, v77, v78
	v_exp_f32_e32 v76, v76
	v_fmamk_f32 v77, v117, 0x3fb8aa3b, v106
	v_exp_f32_e32 v77, v77
	v_fmamk_f32 v78, v110, 0x3fb8aa3b, v106
	v_add_f32_e32 v75, v74, v79
	v_exp_f32_e32 v78, v78
	v_fmamk_f32 v79, v112, 0x3fb8aa3b, v106
	v_exp_f32_e32 v79, v79
	v_fmamk_f32 v80, v111, 0x3fb8aa3b, v106
	v_add_f32_e32 v75, v76, v75
	v_exp_f32_e32 v80, v80
	v_fmamk_f32 v81, v135, 0x3fb8aa3b, v106
	v_add_f32_e32 v75, v77, v75
	v_exp_f32_e32 v81, v81
	v_fmamk_f32 v82, v113, 0x3fb8aa3b, v106
	v_add_f32_e32 v75, v78, v75
	v_exp_f32_e32 v82, v82
	v_add_f32_e32 v75, v79, v75
	v_add_f32_e32 v75, v80, v75
	v_add_f32_e32 v75, v81, v75
	v_add_f32_e32 v83, v82, v75
	v_cvt_pk_bf16_f32 v74, v74, v76
	v_cvt_pk_bf16_f32 v75, v77, v78
	v_fmamk_f32 v78, v108, 0x3fb8aa3b, v106
	v_exp_f32_e32 v78, v78
	v_cvt_pk_bf16_f32 v76, v79, v80
	v_fmamk_f32 v80, v107, 0x3fb8aa3b, v106
	v_cvt_pk_bf16_f32 v77, v81, v82
	v_exp_f32_e32 v80, v80
	v_fmamk_f32 v81, v109, 0x3fb8aa3b, v106
	v_exp_f32_e32 v81, v81
	v_fmamk_f32 v82, v102, 0x3fb8aa3b, v106
	v_add_f32_e32 v79, v78, v83
	v_exp_f32_e32 v82, v82
	v_fmamk_f32 v83, v104, 0x3fb8aa3b, v106
	v_exp_f32_e32 v83, v83
	v_fmamk_f32 v84, v103, 0x3fb8aa3b, v106
	v_add_f32_e32 v79, v80, v79
	v_exp_f32_e32 v84, v84
	v_fmamk_f32 v85, v105, 0x3fb8aa3b, v106
	v_add_f32_e32 v79, v81, v79
	v_exp_f32_e32 v85, v85
	v_fmamk_f32 v99, v99, 0x3fb8aa3b, v106
	v_add_f32_e32 v79, v82, v79
	v_exp_f32_e32 v99, v99
	v_add_f32_e32 v79, v83, v79
	v_add_f32_e32 v79, v84, v79
	v_add_f32_e32 v79, v85, v79
	v_add_f32_e32 v102, v99, v79
	v_cvt_pk_bf16_f32 v78, v78, v80
	v_cvt_pk_bf16_f32 v79, v81, v82
	v_fmamk_f32 v82, v100, 0x3fb8aa3b, v106
	v_cvt_pk_bf16_f32 v80, v83, v84
	v_exp_f32_e32 v82, v82
	v_fmamk_f32 v84, v98, 0x3fb8aa3b, v106
	v_cvt_pk_bf16_f32 v81, v85, v99
	v_exp_f32_e32 v84, v84
	v_fmamk_f32 v85, v101, 0x3fb8aa3b, v106
	v_exp_f32_e32 v85, v85
	v_fmamk_f32 v94, v94, 0x3fb8aa3b, v106
	v_exp_f32_e32 v94, v94
	v_fmamk_f32 v96, v96, 0x3fb8aa3b, v106
	v_add_f32_e32 v83, v82, v102
	v_exp_f32_e32 v96, v96
	v_fmamk_f32 v95, v95, 0x3fb8aa3b, v106
	v_add_f32_e32 v83, v84, v83
	v_exp_f32_e32 v95, v95
	v_fmamk_f32 v97, v97, 0x3fb8aa3b, v106
	v_add_f32_e32 v83, v85, v83
	v_exp_f32_e32 v97, v97
	v_fmamk_f32 v91, v91, 0x3fb8aa3b, v106
	v_add_f32_e32 v83, v94, v83
	v_exp_f32_e32 v91, v91
	v_add_f32_e32 v83, v96, v83
	v_add_f32_e32 v83, v95, v83
	v_add_f32_e32 v83, v97, v83
	v_add_f32_e32 v98, v91, v83
	v_cvt_pk_bf16_f32 v82, v82, v84
	v_cvt_pk_bf16_f32 v83, v85, v94
	v_cvt_pk_bf16_f32 v84, v96, v95
	v_cvt_pk_bf16_f32 v85, v97, v91
	v_fmamk_f32 v91, v92, 0x3fb8aa3b, v106
	v_exp_f32_e32 v91, v91
	v_fmamk_f32 v90, v90, 0x3fb8aa3b, v106
	v_exp_f32_e32 v90, v90
	v_fmamk_f32 v93, v93, 0x3fb8aa3b, v106
	v_exp_f32_e32 v93, v93
	v_fmamk_f32 v86, v86, 0x3fb8aa3b, v106
	v_exp_f32_e32 v94, v86
	v_add_f32_e32 v92, v91, v98
	v_add_f32_e32 v92, v90, v92
	v_fmamk_f32 v88, v88, 0x3fb8aa3b, v106
	v_add_f32_e32 v92, v93, v92
	v_exp_f32_e32 v88, v88
	v_fmamk_f32 v87, v87, 0x3fb8aa3b, v106
	v_add_f32_e32 v86, v94, v92
	v_exp_f32_e32 v92, v87
	v_fmamk_f32 v87, v138, 0x3fb8aa3b, v106
	v_exp_f32_e32 v95, v87
	v_fmamk_f32 v87, v89, 0x3fb8aa3b, v106
	v_exp_f32_e32 v89, v87
	v_add_f32_e32 v86, v88, v86
	v_add_f32_e32 v86, v92, v86
	v_add_f32_e32 v86, v95, v86
	v_add_f32_e32 v96, v89, v86
	v_cvt_pk_bf16_f32 v86, v91, v90
	v_fmamk_f32 v90, v137, 0x3fb8aa3b, v106
	v_cvt_pk_bf16_f32 v87, v93, v94
	v_cvt_pk_bf16_f32 v88, v88, v92
	v_exp_f32_e32 v90, v90
	v_fmamk_f32 v92, v136, 0x3fb8aa3b, v106
	v_exp_f32_e32 v92, v92
	v_fmamk_f32 v93, v141, 0x3fb8aa3b, v106
	v_exp_f32_e32 v93, v93
	v_fmamk_f32 v94, v139, 0x3fb8aa3b, v106
	v_cvt_pk_bf16_f32 v89, v95, v89
	v_exp_f32_e32 v95, v94
; __device__ __forceinline__ unsigned cvt_pk_bf16(float lo, float hi) { unsigned r; asm volatile("v_cvt_pk_bf16_f32 %0, %1, %2" : "=v"(r) : "v"(lo), "v"(hi)); return r; }
; __device__ __forceinline__ float fast_exp2(float x) { return __builtin_amdgcn_exp2f(x); }
; template <bool LOCAL>
; __device__ __forceinline__ void attn_unit(const bf16_t* Q, const bf16_t* KT, const bf16_t* VT, bf16_t* O, LAS unsigned char* lds, int b, int h, int r, int w, int tq, int lane) {
;     ...
;     float sum = 0.f; const float mxl = mx * 1.4426950408889634f;
;     bf16x8 pb[NP];
; #pragma unroll
;     for (int p = 0; p < NP; ++p) { float e[8];
; #pragma unroll
;         for (int f = 0; f < 2; ++f)
; #pragma unroll
;             for (int j = 0; j < 4; ++j) { e[4 * f + j] = fast_exp2(fmaf(s[2 * p + f][j], 1.4426950408889634f, -mxl)); sum += e[4 * f + j]; }
;         u32x4 pw; pw.x = cvt_pk_bf16(e[0], e[1]); pw.y = cvt_pk_bf16(e[2], e[3]); pw.z = cvt_pk_bf16(e[4], e[5]); pw.w = cvt_pk_bf16(e[6], e[7]);
;         pb[p] = __builtin_bit_cast(bf16x8, pw); }
	v_fmamk_f32 v94, v195, 0x3fb8aa3b, v106
	v_add_f32_e32 v91, v90, v96
	v_exp_f32_e32 v96, v94
	v_fmamk_f32 v94, v140, 0x3fb8aa3b, v106
	v_add_f32_e32 v91, v92, v91
	v_exp_f32_e32 v97, v94
	v_fmamk_f32 v94, v199, 0x3fb8aa3b, v106
	v_add_f32_e32 v91, v93, v91
	v_exp_f32_e32 v98, v94
	v_fmamk_f32 v94, v197, 0x3fb8aa3b, v106
	v_add_f32_e32 v91, v95, v91
	v_exp_f32_e32 v99, v94
	v_cvt_pk_bf16_f32 v94, v90, v92
	v_fmamk_f32 v90, v198, 0x3fb8aa3b, v106
	v_add_f32_e32 v91, v96, v91
	v_exp_f32_e32 v90, v90
	v_fmamk_f32 v92, v196, 0x3fb8aa3b, v106
	v_add_f32_e32 v91, v97, v91
	v_cvt_pk_bf16_f32 v95, v93, v95
	v_exp_f32_e32 v92, v92
	v_fmamk_f32 v93, v202, 0x3fb8aa3b, v106
	v_add_f32_e32 v91, v98, v91
	v_cvt_pk_bf16_f32 v96, v96, v97
	v_cvt_pk_bf16_f32 v97, v98, v99
	v_exp_f32_e32 v93, v93
	v_fmamk_f32 v98, v200, 0x3fb8aa3b, v106
	v_add_f32_e32 v91, v99, v91
	v_exp_f32_e32 v98, v98
	v_fmamk_f32 v99, v203, 0x3fb8aa3b, v106
	v_add_f32_e32 v91, v90, v91
	v_exp_f32_e32 v99, v99
	v_fmamk_f32 v100, v201, 0x3fb8aa3b, v106
	v_add_f32_e32 v91, v92, v91
	v_exp_f32_e32 v100, v100
	v_fmamk_f32 v101, v205, 0x3fb8aa3b, v106
	v_add_f32_e32 v91, v93, v91
	v_exp_f32_e32 v101, v101
	v_fmamk_f32 v102, v204, 0x3fb8aa3b, v106
	v_add_f32_e32 v91, v98, v91
	v_exp_f32_e32 v105, v102
	v_fmamk_f32 v2, v2, 0x3fb8aa3b, v106
	v_add_f32_e32 v91, v99, v91
	v_exp_f32_e32 v2, v2
	v_fmamk_f32 v3, v3, 0x3fb8aa3b, v106
	v_add_f32_e32 v91, v100, v91
	v_exp_f32_e32 v3, v3
	v_fmamk_f32 v4, v4, 0x3fb8aa3b, v106
	v_add_f32_e32 v91, v101, v91
	v_exp_f32_e32 v4, v4
	v_fmamk_f32 v5, v5, 0x3fb8aa3b, v106
	v_add_f32_e32 v91, v105, v91
	v_exp_f32_e32 v5, v5
	v_fmamk_f32 v10, v10, 0x3fb8aa3b, v106
	v_cvt_pk_bf16_f32 v102, v90, v92
	v_add_f32_e32 v90, v2, v91
	v_exp_f32_e32 v10, v10
	v_fmamk_f32 v11, v11, 0x3fb8aa3b, v106
	v_add_f32_e32 v90, v3, v90
	v_exp_f32_e32 v11, v11
	v_fmamk_f32 v12, v12, 0x3fb8aa3b, v106
	v_add_f32_e32 v90, v4, v90
	v_exp_f32_e32 v12, v12
	v_fmamk_f32 v13, v13, 0x3fb8aa3b, v106
	v_cvt_pk_bf16_f32 v103, v93, v98
	v_cvt_pk_bf16_f32 v104, v99, v100
	v_cvt_pk_bf16_f32 v105, v101, v105
	v_add_f32_e32 v90, v5, v90
	v_exp_f32_e32 v13, v13
	v_cvt_pk_bf16_f32 v98, v2, v3
	v_fmamk_f32 v2, v6, 0x3fb8aa3b, v106
	v_add_f32_e32 v90, v10, v90
	v_cvt_pk_bf16_f32 v99, v4, v5
	v_exp_f32_e32 v2, v2
	v_fmamk_f32 v4, v7, 0x3fb8aa3b, v106
	v_add_f32_e32 v90, v11, v90
	v_exp_f32_e32 v4, v4
	v_fmamk_f32 v5, v8, 0x3fb8aa3b, v106
	v_add_f32_e32 v90, v12, v90
	v_exp_f32_e32 v5, v5
	v_fmamk_f32 v6, v9, 0x3fb8aa3b, v106
	v_add_f32_e32 v90, v13, v90
	v_exp_f32_e32 v6, v6
	v_fmamk_f32 v7, v18, 0x3fb8aa3b, v106
	v_add_f32_e32 v3, v2, v90
	v_exp_f32_e32 v7, v7
	v_fmamk_f32 v8, v19, 0x3fb8aa3b, v106
	v_add_f32_e32 v3, v4, v3
	v_exp_f32_e32 v8, v8
	v_fmamk_f32 v9, v20, 0x3fb8aa3b, v106
	v_cvt_pk_bf16_f32 v100, v10, v11
	v_add_f32_e32 v3, v5, v3
	v_exp_f32_e32 v9, v9
	v_fmamk_f32 v10, v21, 0x3fb8aa3b, v106
	v_cvt_pk_bf16_f32 v101, v12, v13
	v_add_f32_e32 v3, v6, v3
	v_exp_f32_e32 v10, v10
	v_cvt_pk_bf16_f32 v90, v2, v4
	v_fmamk_f32 v2, v14, 0x3fb8aa3b, v106
	v_add_f32_e32 v3, v7, v3
	v_exp_f32_e32 v2, v2
	v_fmamk_f32 v4, v15, 0x3fb8aa3b, v106
	v_add_f32_e32 v3, v8, v3
	v_cvt_pk_bf16_f32 v91, v5, v6
	v_exp_f32_e32 v4, v4
	v_fmamk_f32 v5, v16, 0x3fb8aa3b, v106
	v_add_f32_e32 v3, v9, v3
	v_exp_f32_e32 v5, v5
	v_fmamk_f32 v6, v17, 0x3fb8aa3b, v106
	v_add_f32_e32 v3, v10, v3
	v_cvt_pk_bf16_f32 v92, v7, v8
	v_exp_f32_e32 v6, v6
	v_fmamk_f32 v7, v26, 0x3fb8aa3b, v106
	v_add_f32_e32 v3, v2, v3
	v_exp_f32_e32 v7, v7
	v_fmamk_f32 v8, v27, 0x3fb8aa3b, v106
	v_cvt_pk_bf16_f32 v93, v9, v10
	v_add_f32_e32 v3, v4, v3
	v_exp_f32_e32 v8, v8
	v_fmamk_f32 v9, v28, 0x3fb8aa3b, v106
	v_add_f32_e32 v3, v5, v3
	v_exp_f32_e32 v9, v9
	v_fmamk_f32 v10, v29, 0x3fb8aa3b, v106
	v_add_f32_e32 v3, v6, v3
	v_exp_f32_e32 v10, v10
	v_cvt_pk_bf16_f32 v26, v2, v4
	v_fmamk_f32 v2, v22, 0x3fb8aa3b, v106
	v_add_f32_e32 v3, v7, v3
	v_exp_f32_e32 v2, v2
	v_fmamk_f32 v4, v23, 0x3fb8aa3b, v106
	v_add_f32_e32 v3, v8, v3
	v_cvt_pk_bf16_f32 v27, v5, v6
	v_exp_f32_e32 v4, v4
	v_fmamk_f32 v5, v24, 0x3fb8aa3b, v106
	v_add_f32_e32 v3, v9, v3
	v_exp_f32_e32 v5, v5
	v_fmamk_f32 v6, v25, 0x3fb8aa3b, v106
	v_add_f32_e32 v3, v10, v3
	v_cvt_pk_bf16_f32 v28, v7, v8
	v_exp_f32_e32 v6, v6
	v_fmamk_f32 v7, v34, 0x3fb8aa3b, v106
	v_add_f32_e32 v3, v2, v3
	v_exp_f32_e32 v7, v7
	v_fmamk_f32 v8, v35, 0x3fb8aa3b, v106
	v_cvt_pk_bf16_f32 v29, v9, v10
	v_add_f32_e32 v3, v4, v3
	v_exp_f32_e32 v8, v8
	v_fmamk_f32 v9, v36, 0x3fb8aa3b, v106
	v_add_f32_e32 v3, v5, v3
	v_exp_f32_e32 v9, v9
	v_fmamk_f32 v10, v37, 0x3fb8aa3b, v106
	v_add_f32_e32 v3, v6, v3
	v_exp_f32_e32 v13, v10
	v_cvt_pk_bf16_f32 v10, v2, v4
	v_fmamk_f32 v2, v30, 0x3fb8aa3b, v106
	v_add_f32_e32 v3, v7, v3
	v_exp_f32_e32 v2, v2
	v_fmamk_f32 v4, v31, 0x3fb8aa3b, v106
	v_add_f32_e32 v3, v8, v3
	v_cvt_pk_bf16_f32 v11, v5, v6
	v_exp_f32_e32 v4, v4
	v_fmamk_f32 v5, v32, 0x3fb8aa3b, v106
	v_add_f32_e32 v3, v9, v3
	v_exp_f32_e32 v5, v5
	v_fmamk_f32 v6, v33, 0x3fb8aa3b, v106
	v_add_f32_e32 v3, v13, v3
	v_cvt_pk_bf16_f32 v12, v7, v8
	v_exp_f32_e32 v6, v6
	v_fmamk_f32 v7, v42, 0x3fb8aa3b, v106
	v_add_f32_e32 v3, v2, v3
	v_exp_f32_e32 v7, v7
	v_fmamk_f32 v8, v43, 0x3fb8aa3b, v106
	v_cvt_pk_bf16_f32 v13, v9, v13
	v_add_f32_e32 v3, v4, v3
	v_exp_f32_e32 v8, v8
	v_fmamk_f32 v9, v44, 0x3fb8aa3b, v106
	v_add_f32_e32 v3, v5, v3
	v_exp_f32_e32 v9, v9
	v_fmamk_f32 v14, v45, 0x3fb8aa3b, v106
	v_add_f32_e32 v3, v6, v3
	v_exp_f32_e32 v14, v14
	v_add_f32_e32 v3, v7, v3
	v_add_f32_e32 v3, v8, v3
	v_add_f32_e32 v3, v9, v3
	v_add_f32_e32 v15, v14, v3
	v_cvt_pk_bf16_f32 v2, v2, v4
	v_cvt_pk_bf16_f32 v3, v5, v6
	v_fmamk_f32 v6, v38, 0x3fb8aa3b, v106
; __device__ __forceinline__ unsigned cvt_pk_bf16(float lo, float hi) { unsigned r; asm volatile("v_cvt_pk_bf16_f32 %0, %1, %2" : "=v"(r) : "v"(lo), "v"(hi)); return r; }
; __device__ __forceinline__ float fast_exp2(float x) { return __builtin_amdgcn_exp2f(x); }
; #define ATT_VLOAD(buf, p) do { const bf16_t* vp_ = vloc + (size_t)((p) * 8 * NH) * 1024; \
;         _Pragma("unroll") for (int df = 0; df < 8; ++df) va[buf][df] = *(const bf16x8*)(vp_ + df * 128); } while (0)
; template <bool LOCAL>
; __device__ __forceinline__ void attn_unit(const bf16_t* Q, const bf16_t* KT, const bf16_t* VT, bf16_t* O, LAS unsigned char* lds, int b, int h, int r, int w, int tq, int lane) {
;     ...
;             for (int j = 0; j < 4; ++j) { e[4 * f + j] = fast_exp2(fmaf(s[2 * p + f][j], 1.4426950408889634f, -mxl)); sum += e[4 * f + j]; }
;         u32x4 pw; pw.x = cvt_pk_bf16(e[0], e[1]); pw.y = cvt_pk_bf16(e[2], e[3]); pw.z = cvt_pk_bf16(e[4], e[5]); pw.w = cvt_pk_bf16(e[6], e[7]);
;         pb[p] = __builtin_bit_cast(bf16x8, pw); }
;     sum += __shfl_xor(sum, 16); sum += __shfl_xor(sum, 32);
;     f32x4 o[8];
; #pragma unroll
;     for (int df = 0; df < 8; ++df) o[df] = (f32x4){0.f, 0.f, 0.f, 0.f};
;     if (LOCAL) {
;         const bf16_t* vloc = VT + ((size_t)(((rgl >> 3) + g) * NH + h)) * 1024 + q * 8;
;         bf16x8 va[2][8];
;     ...
;         ATT_VLOAD(0, 0);
; #pragma unroll
;         for (int p = 0; p < 8; ++p) {
;             __builtin_amdgcn_s_barrier();
;             if (p + 1 < 8) ATT_VLOAD((p + 1) & 1, p + 1);
;             __builtin_amdgcn_sched_barrier(0);
; #pragma unroll
;             for (int df = 0; df < 8; ++df) o[df] = __builtin_amdgcn_mfma_f32_16x16x32_bf16(va[p & 1][df], pb[p], o[df], 0, 0, 0);
;             __builtin_amdgcn_sched_barrier(0);
;         }
;     ...
;     }
	v_exp_f32_e32 v6, v6
	v_cvt_pk_bf16_f32 v4, v7, v8
	v_fmamk_f32 v8, v39, 0x3fb8aa3b, v106
	v_cvt_pk_bf16_f32 v5, v9, v14
	v_exp_f32_e32 v8, v8
	v_fmamk_f32 v9, v40, 0x3fb8aa3b, v106
	v_exp_f32_e32 v9, v9
	v_fmamk_f32 v14, v41, 0x3fb8aa3b, v106
	v_add_f32_e32 v7, v6, v15
	v_exp_f32_e32 v14, v14
	v_fmamk_f32 v15, v50, 0x3fb8aa3b, v106
	v_exp_f32_e32 v15, v15
	v_fmamk_f32 v16, v51, 0x3fb8aa3b, v106
	v_add_f32_e32 v7, v8, v7
	v_exp_f32_e32 v16, v16
	v_fmamk_f32 v17, v52, 0x3fb8aa3b, v106
	v_add_f32_e32 v7, v9, v7
	v_exp_f32_e32 v17, v17
	v_fmamk_f32 v18, v53, 0x3fb8aa3b, v106
	v_add_f32_e32 v7, v14, v7
	v_exp_f32_e32 v18, v18
	v_add_f32_e32 v7, v15, v7
	v_add_f32_e32 v7, v16, v7
	v_add_f32_e32 v7, v17, v7
	v_add_f32_e32 v19, v18, v7
	v_cvt_pk_bf16_f32 v6, v6, v8
	v_cvt_pk_bf16_f32 v7, v9, v14
	v_fmamk_f32 v14, v46, 0x3fb8aa3b, v106
	v_exp_f32_e32 v14, v14
	v_cvt_pk_bf16_f32 v8, v15, v16
	v_fmamk_f32 v16, v47, 0x3fb8aa3b, v106
	v_cvt_pk_bf16_f32 v9, v17, v18
	v_exp_f32_e32 v16, v16
	v_fmamk_f32 v17, v48, 0x3fb8aa3b, v106
	v_exp_f32_e32 v17, v17
	v_fmamk_f32 v18, v49, 0x3fb8aa3b, v106
	v_add_f32_e32 v15, v14, v19
	v_exp_f32_e32 v18, v18
	v_fmamk_f32 v19, v58, 0x3fb8aa3b, v106
	v_exp_f32_e32 v19, v19
	v_fmamk_f32 v20, v59, 0x3fb8aa3b, v106
	v_add_f32_e32 v15, v16, v15
	v_exp_f32_e32 v20, v20
	v_fmamk_f32 v21, v60, 0x3fb8aa3b, v106
	v_add_f32_e32 v15, v17, v15
	v_exp_f32_e32 v21, v21
	v_fmamk_f32 v22, v61, 0x3fb8aa3b, v106
	v_add_f32_e32 v15, v18, v15
	v_exp_f32_e32 v22, v22
	v_add_f32_e32 v15, v19, v15
	v_add_f32_e32 v15, v20, v15
	v_add_f32_e32 v15, v21, v15
	v_add_f32_e32 v23, v22, v15
	v_cvt_pk_bf16_f32 v14, v14, v16
	v_cvt_pk_bf16_f32 v15, v17, v18
	v_fmamk_f32 v18, v54, 0x3fb8aa3b, v106
	v_exp_f32_e32 v18, v18
	v_cvt_pk_bf16_f32 v16, v19, v20
	v_fmamk_f32 v20, v55, 0x3fb8aa3b, v106
	v_cvt_pk_bf16_f32 v17, v21, v22
	v_exp_f32_e32 v20, v20
	v_fmamk_f32 v21, v56, 0x3fb8aa3b, v106
	v_exp_f32_e32 v21, v21
	v_fmamk_f32 v22, v57, 0x3fb8aa3b, v106
	v_add_f32_e32 v19, v18, v23
	v_exp_f32_e32 v22, v22
	v_fmamk_f32 v23, v62, 0x3fb8aa3b, v106
	v_exp_f32_e32 v23, v23
	v_fmamk_f32 v24, v63, 0x3fb8aa3b, v106
	v_add_f32_e32 v19, v20, v19
	v_exp_f32_e32 v24, v24
	v_fmamk_f32 v25, v64, 0x3fb8aa3b, v106
	v_add_f32_e32 v19, v21, v19
	v_exp_f32_e32 v25, v25
	v_fmac_f32_e32 v106, 0x3fb8aa3b, v65
	v_add_f32_e32 v19, v22, v19
	v_exp_f32_e32 v30, v106
	v_add_f32_e32 v19, v23, v19
	v_add_f32_e32 v19, v24, v19
	v_add_f32_e32 v19, v25, v19
	v_add_f32_e32 v31, v30, v19
	v_cvt_pk_bf16_f32 v18, v18, v20
	v_cvt_pk_bf16_f32 v19, v21, v22
	ds_bpermute_b32 v22, v181, v31
	v_cvt_pk_bf16_f32 v20, v23, v24
	v_cvt_pk_bf16_f32 v21, v25, v30
	s_waitcnt lgkmcnt(0)
	v_add_f32_e32 v134, v31, v22
	v_add_u32_e32 v22, v194, v165
	v_lshl_or_b32 v22, v22, 4, s72
	v_ashrrev_i32_e32 v23, 31, v22
	v_lshlrev_b64 v[22:23], 11, v[22:23]
	v_lshl_add_u64 v[132:133], v[148:149], 0, v[22:23]
	v_add_co_u32_e32 v54, vcc, s6, v132
	global_load_dwordx4 v[58:61], v[132:133], off
	global_load_dwordx4 v[62:65], v[132:133], off offset:256
	global_load_dwordx4 v[106:109], v[132:133], off offset:512
	global_load_dwordx4 v[110:113], v[132:133], off offset:768
	global_load_dwordx4 v[114:117], v[132:133], off offset:1024
	global_load_dwordx4 v[118:121], v[132:133], off offset:1280
	global_load_dwordx4 v[122:125], v[132:133], off offset:1536
	global_load_dwordx4 v[126:129], v[132:133], off offset:1792
	v_addc_co_u32_e32 v55, vcc, 0, v133, vcc
	s_barrier
	global_load_dwordx4 v[22:25], v[54:55], off
	global_load_dwordx4 v[30:33], v[54:55], off offset:256
	global_load_dwordx4 v[34:37], v[54:55], off offset:512
	global_load_dwordx4 v[38:41], v[54:55], off offset:768
	global_load_dwordx4 v[42:45], v[54:55], off offset:1024
	global_load_dwordx4 v[46:49], v[54:55], off offset:1280
	global_load_dwordx4 v[50:53], v[54:55], off offset:1536
	s_nop 0
	global_load_dwordx4 v[54:57], v[54:55], off offset:1792
	ds_bpermute_b32 v135, v182, v134
	s_waitcnt vmcnt(15)
	v_mfma_f32_16x16x32_bf16 v[58:61], v[58:61], v[66:69], 0
	s_waitcnt vmcnt(14)
	v_mfma_f32_16x16x32_bf16 v[62:65], v[62:65], v[66:69], 0
	s_waitcnt vmcnt(13)
	v_mfma_f32_16x16x32_bf16 v[106:109], v[106:109], v[66:69], 0
	s_waitcnt vmcnt(12)
	v_mfma_f32_16x16x32_bf16 v[110:113], v[110:113], v[66:69], 0
	s_waitcnt vmcnt(11)
	v_mfma_f32_16x16x32_bf16 v[114:117], v[114:117], v[66:69], 0
	s_waitcnt vmcnt(10)
	v_mfma_f32_16x16x32_bf16 v[118:121], v[118:121], v[66:69], 0
	s_waitcnt vmcnt(9)
	v_mfma_f32_16x16x32_bf16 v[122:125], v[122:125], v[66:69], 0
	s_waitcnt vmcnt(8)
	v_mfma_f32_16x16x32_bf16 v[66:69], v[126:129], v[66:69], 0
	v_add_co_u32_e32 v140, vcc, s7, v132
	s_barrier
	s_nop 0
	v_addc_co_u32_e32 v141, vcc, 0, v133, vcc
	global_load_dwordx4 v[126:129], v[140:141], off
	global_load_dwordx4 v[136:139], v[140:141], off offset:256
	global_load_dwordx4 v[194:197], v[140:141], off offset:512
	global_load_dwordx4 v[198:201], v[140:141], off offset:768
	global_load_dwordx4 v[202:205], v[140:141], off offset:1024
	global_load_dwordx4 v[206:209], v[140:141], off offset:1280
	global_load_dwordx4 v[210:213], v[140:141], off offset:1536
	global_load_dwordx4 v[214:217], v[140:141], off offset:1792
	s_waitcnt vmcnt(15)
	v_mfma_f32_16x16x32_bf16 v[22:25], v[22:25], v[70:73], v[58:61]
	s_waitcnt vmcnt(14)
	v_mfma_f32_16x16x32_bf16 v[30:33], v[30:33], v[70:73], v[62:65]
	s_waitcnt vmcnt(13)
	v_mfma_f32_16x16x32_bf16 v[34:37], v[34:37], v[70:73], v[106:109]
	s_waitcnt vmcnt(12)
	v_mfma_f32_16x16x32_bf16 v[38:41], v[38:41], v[70:73], v[110:113]
	s_waitcnt vmcnt(11)
	v_mfma_f32_16x16x32_bf16 v[42:45], v[42:45], v[70:73], v[114:117]
	s_waitcnt vmcnt(10)
	v_mfma_f32_16x16x32_bf16 v[46:49], v[46:49], v[70:73], v[118:121]
	s_waitcnt vmcnt(9)
	v_mfma_f32_16x16x32_bf16 v[50:53], v[50:53], v[70:73], v[122:125]
	s_waitcnt vmcnt(8)
	v_mfma_f32_16x16x32_bf16 v[54:57], v[54:57], v[70:73], v[66:69]
	v_add_co_u32_e32 v118, vcc, s2, v132
	s_barrier
; #define ATT_VLOAD(buf, p) do { const bf16_t* vp_ = vloc + (size_t)((p) * 8 * NH) * 1024; \
;         _Pragma("unroll") for (int df = 0; df < 8; ++df) va[buf][df] = *(const bf16x8*)(vp_ + df * 128); } while (0)
; template <bool LOCAL>
; __device__ __forceinline__ void attn_unit(const bf16_t* Q, const bf16_t* KT, const bf16_t* VT, bf16_t* O, LAS unsigned char* lds, int b, int h, int r, int w, int tq, int lane) {
;     ...
;     if (LOCAL) {
;         const bf16_t* vloc = VT + ((size_t)(((rgl >> 3) + g) * NH + h)) * 1024 + q * 8;
;         bf16x8 va[2][8];
;     ...
;         ATT_VLOAD(0, 0);
; #pragma unroll
;         for (int p = 0; p < 8; ++p) {
;             __builtin_amdgcn_s_barrier();
;             if (p + 1 < 8) ATT_VLOAD((p + 1) & 1, p + 1);
;             __builtin_amdgcn_sched_barrier(0);
; #pragma unroll
;             for (int df = 0; df < 8; ++df) o[df] = __builtin_amdgcn_mfma_f32_16x16x32_bf16(va[p & 1][df], pb[p], o[df], 0, 0, 0);
;             __builtin_amdgcn_sched_barrier(0);
;         }
;     ...
;     }
	s_nop 0
	v_addc_co_u32_e32 v119, vcc, 0, v133, vcc
	global_load_dwordx4 v[58:61], v[118:119], off
	global_load_dwordx4 v[62:65], v[118:119], off offset:256
	global_load_dwordx4 v[66:69], v[118:119], off offset:512
	global_load_dwordx4 v[70:73], v[118:119], off offset:768
	global_load_dwordx4 v[106:109], v[118:119], off offset:1024
	global_load_dwordx4 v[110:113], v[118:119], off offset:1280
	global_load_dwordx4 v[114:117], v[118:119], off offset:1536
	s_nop 0
	global_load_dwordx4 v[118:121], v[118:119], off offset:1792
	s_waitcnt vmcnt(15)
	v_mfma_f32_16x16x32_bf16 v[22:25], v[126:129], v[74:77], v[22:25]
	s_waitcnt vmcnt(14)
	v_mfma_f32_16x16x32_bf16 v[30:33], v[136:139], v[74:77], v[30:33]
	s_waitcnt vmcnt(13)
	v_mfma_f32_16x16x32_bf16 v[34:37], v[194:197], v[74:77], v[34:37]
	s_waitcnt vmcnt(12)
	v_mfma_f32_16x16x32_bf16 v[38:41], v[198:201], v[74:77], v[38:41]
	s_waitcnt vmcnt(11)
	v_mfma_f32_16x16x32_bf16 v[42:45], v[202:205], v[74:77], v[42:45]
	s_waitcnt vmcnt(10)
	v_mfma_f32_16x16x32_bf16 v[46:49], v[206:209], v[74:77], v[46:49]
	s_waitcnt vmcnt(9)
	v_mfma_f32_16x16x32_bf16 v[50:53], v[210:213], v[74:77], v[50:53]
	s_waitcnt vmcnt(8)
	v_mfma_f32_16x16x32_bf16 v[54:57], v[214:217], v[74:77], v[54:57]
	v_add_co_u32_e32 v140, vcc, s60, v132
	s_barrier
	s_nop 0
	v_addc_co_u32_e32 v141, vcc, 0, v133, vcc
	global_load_dwordx4 v[74:77], v[140:141], off
	global_load_dwordx4 v[122:125], v[140:141], off offset:256
	global_load_dwordx4 v[126:129], v[140:141], off offset:512
	global_load_dwordx4 v[136:139], v[140:141], off offset:768
	global_load_dwordx4 v[194:197], v[140:141], off offset:1024
	global_load_dwordx4 v[198:201], v[140:141], off offset:1280
	global_load_dwordx4 v[202:205], v[140:141], off offset:1536
	global_load_dwordx4 v[206:209], v[140:141], off offset:1792
	s_waitcnt vmcnt(15)
	v_mfma_f32_16x16x32_bf16 v[22:25], v[58:61], v[78:81], v[22:25]
	s_waitcnt vmcnt(14)
	v_mfma_f32_16x16x32_bf16 v[30:33], v[62:65], v[78:81], v[30:33]
	s_waitcnt vmcnt(13)
	v_mfma_f32_16x16x32_bf16 v[34:37], v[66:69], v[78:81], v[34:37]
	s_waitcnt vmcnt(12)
	v_mfma_f32_16x16x32_bf16 v[38:41], v[70:73], v[78:81], v[38:41]
	s_waitcnt vmcnt(11)
	v_mfma_f32_16x16x32_bf16 v[42:45], v[106:109], v[78:81], v[42:45]
	s_waitcnt vmcnt(10)
	v_mfma_f32_16x16x32_bf16 v[46:49], v[110:113], v[78:81], v[46:49]
	s_waitcnt vmcnt(9)
	v_mfma_f32_16x16x32_bf16 v[50:53], v[114:117], v[78:81], v[50:53]
	s_waitcnt vmcnt(8)
	v_mfma_f32_16x16x32_bf16 v[54:57], v[118:121], v[78:81], v[54:57]
	v_add_co_u32_e32 v114, vcc, s61, v132
	s_barrier
	s_nop 0
	v_addc_co_u32_e32 v115, vcc, 0, v133, vcc
	global_load_dwordx4 v[58:61], v[114:115], off
	global_load_dwordx4 v[62:65], v[114:115], off offset:256
	global_load_dwordx4 v[66:69], v[114:115], off offset:512
	global_load_dwordx4 v[70:73], v[114:115], off offset:768
	global_load_dwordx4 v[78:81], v[114:115], off offset:1024
	global_load_dwordx4 v[106:109], v[114:115], off offset:1280
	global_load_dwordx4 v[110:113], v[114:115], off offset:1536
	s_nop 0
	global_load_dwordx4 v[114:117], v[114:115], off offset:1792
	s_waitcnt vmcnt(15)
	v_mfma_f32_16x16x32_bf16 v[22:25], v[74:77], v[82:85], v[22:25]
	s_waitcnt vmcnt(14)
	v_mfma_f32_16x16x32_bf16 v[30:33], v[122:125], v[82:85], v[30:33]
	s_waitcnt vmcnt(13)
	v_mfma_f32_16x16x32_bf16 v[34:37], v[126:129], v[82:85], v[34:37]
	s_waitcnt vmcnt(12)
	v_mfma_f32_16x16x32_bf16 v[38:41], v[136:139], v[82:85], v[38:41]
	s_waitcnt vmcnt(11)
	v_mfma_f32_16x16x32_bf16 v[42:45], v[194:197], v[82:85], v[42:45]
	s_waitcnt vmcnt(10)
	v_mfma_f32_16x16x32_bf16 v[46:49], v[198:201], v[82:85], v[46:49]
	s_waitcnt vmcnt(9)
	v_mfma_f32_16x16x32_bf16 v[50:53], v[202:205], v[82:85], v[50:53]
	s_waitcnt vmcnt(8)
	v_mfma_f32_16x16x32_bf16 v[54:57], v[206:209], v[82:85], v[54:57]
	v_add_co_u32_e32 v140, vcc, s17, v132
	s_barrier
	s_nop 0
	v_addc_co_u32_e32 v141, vcc, 0, v133, vcc
	global_load_dwordx4 v[74:77], v[140:141], off
	global_load_dwordx4 v[82:85], v[140:141], off offset:256
	global_load_dwordx4 v[118:121], v[140:141], off offset:512
	global_load_dwordx4 v[122:125], v[140:141], off offset:768
	global_load_dwordx4 v[126:129], v[140:141], off offset:1024
	global_load_dwordx4 v[136:139], v[140:141], off offset:1280
	global_load_dwordx4 v[194:197], v[140:141], off offset:1536
	global_load_dwordx4 v[198:201], v[140:141], off offset:1792
	s_waitcnt vmcnt(15)
	v_mfma_f32_16x16x32_bf16 v[22:25], v[58:61], v[86:89], v[22:25]
	s_waitcnt vmcnt(14)
	v_mfma_f32_16x16x32_bf16 v[30:33], v[62:65], v[86:89], v[30:33]
	s_waitcnt vmcnt(13)
	v_mfma_f32_16x16x32_bf16 v[34:37], v[66:69], v[86:89], v[34:37]
	s_waitcnt vmcnt(12)
	v_mfma_f32_16x16x32_bf16 v[38:41], v[70:73], v[86:89], v[38:41]
	s_waitcnt vmcnt(11)
	v_mfma_f32_16x16x32_bf16 v[42:45], v[78:81], v[86:89], v[42:45]
	s_waitcnt vmcnt(10)
	v_mfma_f32_16x16x32_bf16 v[46:49], v[106:109], v[86:89], v[46:49]
	s_waitcnt vmcnt(9)
	v_mfma_f32_16x16x32_bf16 v[50:53], v[110:113], v[86:89], v[50:53]
	s_waitcnt vmcnt(8)
	v_mfma_f32_16x16x32_bf16 v[54:57], v[114:117], v[86:89], v[54:57]
	v_add_co_u32_e32 v110, vcc, s62, v132
	s_barrier
; #define LAS __attribute__((address_space(3)))
; #define ATT_VLOAD(buf, p) do { const bf16_t* vp_ = vloc + (size_t)((p) * 8 * NH) * 1024; \
;         _Pragma("unroll") for (int df = 0; df < 8; ++df) va[buf][df] = *(const bf16x8*)(vp_ + df * 128); } while (0)
; template <bool LOCAL>
; __device__ __forceinline__ void attn_unit(const bf16_t* Q, const bf16_t* KT, const bf16_t* VT, bf16_t* O, LAS unsigned char* lds, int b, int h, int r, int w, int tq, int lane) {
;     ...
; #pragma unroll
;         for (int p = 0; p < 8; ++p) {
;             __builtin_amdgcn_s_barrier();
;             if (p + 1 < 8) ATT_VLOAD((p + 1) & 1, p + 1);
;             __builtin_amdgcn_sched_barrier(0);
; #pragma unroll
;             for (int df = 0; df < 8; ++df) o[df] = __builtin_amdgcn_mfma_f32_16x16x32_bf16(va[p & 1][df], pb[p], o[df], 0, 0, 0);
;             __builtin_amdgcn_sched_barrier(0);
;         }
;     ...
;     }
;     {
;         const LAS unsigned char* vl = lds + 65536 + g * 2048 + q * 16;
; #pragma unroll
;         for (int p = 0; p < 8; ++p)
; #pragma unroll
;             for (int df = 0; df < 8; ++df) o[df] = __builtin_amdgcn_mfma_f32_16x16x32_bf16(*(const LAS bf16x8*)(vl + p * 8192 + df * 256), pb[CP + p], o[df], 0, 0, 0);
;     }
	s_nop 0
	v_addc_co_u32_e32 v111, vcc, 0, v133, vcc
	global_load_dwordx4 v[58:61], v[110:111], off
	global_load_dwordx4 v[62:65], v[110:111], off offset:256
	global_load_dwordx4 v[66:69], v[110:111], off offset:512
	global_load_dwordx4 v[70:73], v[110:111], off offset:768
	global_load_dwordx4 v[78:81], v[110:111], off offset:1024
	global_load_dwordx4 v[86:89], v[110:111], off offset:1280
	global_load_dwordx4 v[106:109], v[110:111], off offset:1536
	s_nop 0
	global_load_dwordx4 v[110:113], v[110:111], off offset:1792
	s_waitcnt vmcnt(15)
	v_mfma_f32_16x16x32_bf16 v[22:25], v[74:77], v[94:97], v[22:25]
	s_waitcnt vmcnt(14)
	v_mfma_f32_16x16x32_bf16 v[30:33], v[82:85], v[94:97], v[30:33]
	s_waitcnt vmcnt(13)
	v_mfma_f32_16x16x32_bf16 v[34:37], v[118:121], v[94:97], v[34:37]
	s_waitcnt vmcnt(12)
	v_mfma_f32_16x16x32_bf16 v[38:41], v[122:125], v[94:97], v[38:41]
	s_waitcnt vmcnt(11)
	v_mfma_f32_16x16x32_bf16 v[42:45], v[126:129], v[94:97], v[42:45]
	s_waitcnt vmcnt(10)
	v_mfma_f32_16x16x32_bf16 v[46:49], v[136:139], v[94:97], v[46:49]
	s_waitcnt vmcnt(9)
	v_mfma_f32_16x16x32_bf16 v[50:53], v[194:197], v[94:97], v[50:53]
	s_waitcnt vmcnt(8)
	v_mfma_f32_16x16x32_bf16 v[54:57], v[198:201], v[94:97], v[54:57]
	s_barrier
	s_waitcnt vmcnt(7)
	v_mfma_f32_16x16x32_bf16 v[22:25], v[58:61], v[102:105], v[22:25]
	s_waitcnt vmcnt(6)
	v_mfma_f32_16x16x32_bf16 v[30:33], v[62:65], v[102:105], v[30:33]
	s_waitcnt vmcnt(5)
	v_mfma_f32_16x16x32_bf16 v[34:37], v[66:69], v[102:105], v[34:37]
	s_waitcnt vmcnt(4)
	v_mfma_f32_16x16x32_bf16 v[38:41], v[70:73], v[102:105], v[38:41]
	s_waitcnt vmcnt(3)
	v_mfma_f32_16x16x32_bf16 v[42:45], v[78:81], v[102:105], v[42:45]
	s_waitcnt vmcnt(2)
	v_mfma_f32_16x16x32_bf16 v[46:49], v[86:89], v[102:105], v[46:49]
	s_waitcnt vmcnt(1)
	v_mfma_f32_16x16x32_bf16 v[50:53], v[106:109], v[102:105], v[50:53]
	s_waitcnt vmcnt(0)
	v_mfma_f32_16x16x32_bf16 v[54:57], v[110:113], v[102:105], v[54:57]
	s_waitcnt lgkmcnt(0)
	s_add_i32 s48, s48, 2
	s_add_i32 s52, s52, 2
	s_add_i32 s51, s51, -2
	v_add_u32_e32 v162, 0x80, v162
	s_cmp_eq_u32 s48, 8
	ds_read_b128 v[208:211], v178
	ds_read_b128 v[212:215], v178 offset:256
	ds_read_b128 v[216:219], v178 offset:512
	ds_read_b128 v[220:223], v178 offset:768
	ds_read_b128 v[224:227], v178 offset:1024
	ds_read_b128 v[228:231], v178 offset:1280
	ds_read_b128 v[232:235], v178 offset:1536
	ds_read_b128 v[246:249], v178 offset:1792
	s_waitcnt lgkmcnt(7)
	v_mfma_f32_16x16x32_bf16 v[22:25], v[208:211], v[98:101], v[22:25]
	ds_read_b128 v[208:211], v178 offset:8192
	s_waitcnt lgkmcnt(7)
	v_mfma_f32_16x16x32_bf16 v[30:33], v[212:215], v[98:101], v[30:33]
	ds_read_b128 v[212:215], v178 offset:8448
	s_waitcnt lgkmcnt(7)
	v_mfma_f32_16x16x32_bf16 v[34:37], v[216:219], v[98:101], v[34:37]
	ds_read_b128 v[216:219], v178 offset:8704
	s_waitcnt lgkmcnt(7)
	v_mfma_f32_16x16x32_bf16 v[38:41], v[220:223], v[98:101], v[38:41]
	ds_read_b128 v[220:223], v178 offset:8960
	s_waitcnt lgkmcnt(7)
	v_mfma_f32_16x16x32_bf16 v[42:45], v[224:227], v[98:101], v[42:45]
	ds_read_b128 v[224:227], v178 offset:9216
	s_waitcnt lgkmcnt(7)
	v_mfma_f32_16x16x32_bf16 v[46:49], v[228:231], v[98:101], v[46:49]
	ds_read_b128 v[228:231], v178 offset:9472
	s_waitcnt lgkmcnt(7)
	v_mfma_f32_16x16x32_bf16 v[50:53], v[232:235], v[98:101], v[50:53]
	ds_read_b128 v[232:235], v178 offset:9728
	s_waitcnt lgkmcnt(7)
	v_mfma_f32_16x16x32_bf16 v[54:57], v[246:249], v[98:101], v[54:57]
	ds_read_b128 v[246:249], v178 offset:9984
	s_waitcnt lgkmcnt(7)
	v_mfma_f32_16x16x32_bf16 v[22:25], v[208:211], v[90:93], v[22:25]
	ds_read_b128 v[208:211], v178 offset:16384
	s_waitcnt lgkmcnt(7)
	v_mfma_f32_16x16x32_bf16 v[30:33], v[212:215], v[90:93], v[30:33]
	ds_read_b128 v[212:215], v178 offset:16640
	s_waitcnt lgkmcnt(7)
	v_mfma_f32_16x16x32_bf16 v[34:37], v[216:219], v[90:93], v[34:37]
	ds_read_b128 v[216:219], v178 offset:16896
	s_waitcnt lgkmcnt(7)
	v_mfma_f32_16x16x32_bf16 v[38:41], v[220:223], v[90:93], v[38:41]
	ds_read_b128 v[220:223], v178 offset:17152
	s_waitcnt lgkmcnt(7)
	v_mfma_f32_16x16x32_bf16 v[42:45], v[224:227], v[90:93], v[42:45]
	ds_read_b128 v[224:227], v178 offset:17408
	s_waitcnt lgkmcnt(7)
	v_mfma_f32_16x16x32_bf16 v[46:49], v[228:231], v[90:93], v[46:49]
	ds_read_b128 v[228:231], v178 offset:17664
	s_waitcnt lgkmcnt(7)
	v_mfma_f32_16x16x32_bf16 v[50:53], v[232:235], v[90:93], v[50:53]
	ds_read_b128 v[232:235], v178 offset:17920
	s_waitcnt lgkmcnt(7)
	v_mfma_f32_16x16x32_bf16 v[54:57], v[246:249], v[90:93], v[54:57]
	ds_read_b128 v[246:249], v178 offset:18176
	s_waitcnt lgkmcnt(7)
	v_mfma_f32_16x16x32_bf16 v[22:25], v[208:211], v[26:29], v[22:25]
	ds_read_b128 v[208:211], v178 offset:24576
	s_waitcnt lgkmcnt(7)
	v_mfma_f32_16x16x32_bf16 v[30:33], v[212:215], v[26:29], v[30:33]
	ds_read_b128 v[212:215], v178 offset:24832
	s_waitcnt lgkmcnt(7)
	v_mfma_f32_16x16x32_bf16 v[34:37], v[216:219], v[26:29], v[34:37]
	ds_read_b128 v[216:219], v178 offset:25088
	s_waitcnt lgkmcnt(7)
	v_mfma_f32_16x16x32_bf16 v[38:41], v[220:223], v[26:29], v[38:41]
	ds_read_b128 v[220:223], v178 offset:25344
	s_waitcnt lgkmcnt(7)
	v_mfma_f32_16x16x32_bf16 v[42:45], v[224:227], v[26:29], v[42:45]
	ds_read_b128 v[224:227], v178 offset:25600
	s_waitcnt lgkmcnt(7)
	v_mfma_f32_16x16x32_bf16 v[46:49], v[228:231], v[26:29], v[46:49]
	ds_read_b128 v[228:231], v178 offset:25856
	s_waitcnt lgkmcnt(7)
	v_mfma_f32_16x16x32_bf16 v[50:53], v[232:235], v[26:29], v[50:53]
	ds_read_b128 v[232:235], v178 offset:26112
	s_waitcnt lgkmcnt(7)
	v_mfma_f32_16x16x32_bf16 v[26:29], v[246:249], v[26:29], v[54:57]
	ds_read_b128 v[246:249], v178 offset:26368
	s_waitcnt lgkmcnt(7)
; #define LAS __attribute__((address_space(3)))
; template <bool LOCAL>
; __device__ __forceinline__ void attn_unit(const bf16_t* Q, const bf16_t* KT, const bf16_t* VT, bf16_t* O, LAS unsigned char* lds, int b, int h, int r, int w, int tq, int lane) {
;     ...
;     {
;         const LAS unsigned char* vl = lds + 65536 + g * 2048 + q * 16;
; #pragma unroll
;         for (int p = 0; p < 8; ++p)
; #pragma unroll
;             for (int df = 0; df < 8; ++df) o[df] = __builtin_amdgcn_mfma_f32_16x16x32_bf16(*(const LAS bf16x8*)(vl + p * 8192 + df * 256), pb[CP + p], o[df], 0, 0, 0);
;     }
	v_mfma_f32_16x16x32_bf16 v[22:25], v[208:211], v[10:13], v[22:25]
	ds_read_b128 v[208:211], v178 offset:32768
	s_waitcnt lgkmcnt(7)
	v_mfma_f32_16x16x32_bf16 v[30:33], v[212:215], v[10:13], v[30:33]
	ds_read_b128 v[212:215], v178 offset:33024
	s_waitcnt lgkmcnt(7)
	v_mfma_f32_16x16x32_bf16 v[34:37], v[216:219], v[10:13], v[34:37]
	ds_read_b128 v[216:219], v178 offset:33280
	s_waitcnt lgkmcnt(7)
	v_mfma_f32_16x16x32_bf16 v[38:41], v[220:223], v[10:13], v[38:41]
	ds_read_b128 v[220:223], v178 offset:33536
	s_waitcnt lgkmcnt(7)
	v_mfma_f32_16x16x32_bf16 v[42:45], v[224:227], v[10:13], v[42:45]
	ds_read_b128 v[224:227], v178 offset:33792
	s_waitcnt lgkmcnt(7)
	v_mfma_f32_16x16x32_bf16 v[46:49], v[228:231], v[10:13], v[46:49]
	ds_read_b128 v[228:231], v178 offset:34048
	s_waitcnt lgkmcnt(7)
	v_mfma_f32_16x16x32_bf16 v[50:53], v[232:235], v[10:13], v[50:53]
	ds_read_b128 v[232:235], v178 offset:34304
	s_waitcnt lgkmcnt(7)
	v_mfma_f32_16x16x32_bf16 v[10:13], v[246:249], v[10:13], v[26:29]
	ds_read_b128 v[246:249], v178 offset:34560
	s_waitcnt lgkmcnt(7)
	v_mfma_f32_16x16x32_bf16 v[22:25], v[208:211], v[2:5], v[22:25]
	ds_read_b128 v[208:211], v178 offset:40960
	s_waitcnt lgkmcnt(7)
	v_mfma_f32_16x16x32_bf16 v[26:29], v[212:215], v[2:5], v[30:33]
	ds_read_b128 v[212:215], v178 offset:41216
	s_waitcnt lgkmcnt(7)
	v_mfma_f32_16x16x32_bf16 v[30:33], v[216:219], v[2:5], v[34:37]
	ds_read_b128 v[216:219], v178 offset:41472
	s_waitcnt lgkmcnt(7)
	v_mfma_f32_16x16x32_bf16 v[34:37], v[220:223], v[2:5], v[38:41]
	ds_read_b128 v[220:223], v178 offset:41728
	s_waitcnt lgkmcnt(7)
	v_mfma_f32_16x16x32_bf16 v[38:41], v[224:227], v[2:5], v[42:45]
	ds_read_b128 v[224:227], v178 offset:41984
	s_waitcnt lgkmcnt(7)
	v_mfma_f32_16x16x32_bf16 v[42:45], v[228:231], v[2:5], v[46:49]
	ds_read_b128 v[228:231], v178 offset:42240
	s_waitcnt lgkmcnt(7)
	v_mfma_f32_16x16x32_bf16 v[46:49], v[232:235], v[2:5], v[50:53]
	ds_read_b128 v[232:235], v178 offset:42496
	s_waitcnt lgkmcnt(7)
	v_mfma_f32_16x16x32_bf16 v[2:5], v[246:249], v[2:5], v[10:13]
	ds_read_b128 v[246:249], v178 offset:42752
	s_waitcnt lgkmcnt(7)
	v_mfma_f32_16x16x32_bf16 v[10:13], v[208:211], v[6:9], v[22:25]
	ds_read_b128 v[208:211], v178 offset:49152
	s_waitcnt lgkmcnt(7)
	v_mfma_f32_16x16x32_bf16 v[22:25], v[212:215], v[6:9], v[26:29]
	ds_read_b128 v[212:215], v178 offset:49408
	s_waitcnt lgkmcnt(7)
	v_mfma_f32_16x16x32_bf16 v[26:29], v[216:219], v[6:9], v[30:33]
	ds_read_b128 v[216:219], v178 offset:49664
	s_waitcnt lgkmcnt(7)
	v_mfma_f32_16x16x32_bf16 v[30:33], v[220:223], v[6:9], v[34:37]
	ds_read_b128 v[220:223], v178 offset:49920
	s_waitcnt lgkmcnt(7)
	v_mfma_f32_16x16x32_bf16 v[34:37], v[224:227], v[6:9], v[38:41]
	ds_read_b128 v[224:227], v178 offset:50176
	s_waitcnt lgkmcnt(7)
	v_mfma_f32_16x16x32_bf16 v[38:41], v[228:231], v[6:9], v[42:45]
	ds_read_b128 v[228:231], v178 offset:50432
	s_waitcnt lgkmcnt(7)
	v_mfma_f32_16x16x32_bf16 v[42:45], v[232:235], v[6:9], v[46:49]
	ds_read_b128 v[232:235], v178 offset:50688
	s_waitcnt lgkmcnt(7)
	v_mfma_f32_16x16x32_bf16 v[2:5], v[246:249], v[6:9], v[2:5]
	ds_read_b128 v[246:249], v178 offset:50944
	s_waitcnt lgkmcnt(7)
	v_mfma_f32_16x16x32_bf16 v[6:9], v[208:211], v[14:17], v[10:13]
	ds_read_b128 v[208:211], v178 offset:57344
	s_waitcnt lgkmcnt(7)
	v_mfma_f32_16x16x32_bf16 v[10:13], v[212:215], v[14:17], v[22:25]
	ds_read_b128 v[212:215], v178 offset:57600
	s_waitcnt lgkmcnt(7)
	v_mfma_f32_16x16x32_bf16 v[22:25], v[216:219], v[14:17], v[26:29]
	ds_read_b128 v[216:219], v178 offset:57856
	s_waitcnt lgkmcnt(7)
	v_mfma_f32_16x16x32_bf16 v[26:29], v[220:223], v[14:17], v[30:33]
	ds_read_b128 v[220:223], v178 offset:58112
	s_waitcnt lgkmcnt(7)
	v_mfma_f32_16x16x32_bf16 v[30:33], v[224:227], v[14:17], v[34:37]
	ds_read_b128 v[224:227], v178 offset:58368
	s_waitcnt lgkmcnt(7)
	v_mfma_f32_16x16x32_bf16 v[34:37], v[228:231], v[14:17], v[38:41]
	ds_read_b128 v[228:231], v178 offset:58624
	s_waitcnt lgkmcnt(7)
	v_mfma_f32_16x16x32_bf16 v[38:41], v[232:235], v[14:17], v[42:45]
	ds_read_b128 v[232:235], v178 offset:58880
	s_waitcnt lgkmcnt(7)
	v_mfma_f32_16x16x32_bf16 v[2:5], v[246:249], v[14:17], v[2:5]
	ds_read_b128 v[246:249], v178 offset:59136
	s_waitcnt lgkmcnt(7)
	v_mfma_f32_16x16x32_bf16 v[6:9], v[208:211], v[18:21], v[6:9]
	s_waitcnt lgkmcnt(6)
	v_mfma_f32_16x16x32_bf16 v[10:13], v[212:215], v[18:21], v[10:13]
	s_waitcnt lgkmcnt(5)
	v_mfma_f32_16x16x32_bf16 v[14:17], v[216:219], v[18:21], v[22:25]
	s_waitcnt lgkmcnt(4)
	v_mfma_f32_16x16x32_bf16 v[22:25], v[220:223], v[18:21], v[26:29]
	s_waitcnt lgkmcnt(3)
	v_mfma_f32_16x16x32_bf16 v[26:29], v[224:227], v[18:21], v[30:33]
	s_waitcnt lgkmcnt(2)
	v_mfma_f32_16x16x32_bf16 v[30:33], v[228:231], v[18:21], v[34:37]
	s_waitcnt lgkmcnt(1)
	v_mfma_f32_16x16x32_bf16 v[34:37], v[232:235], v[18:21], v[38:41]
	s_waitcnt lgkmcnt(0)
; #define LAS __attribute__((address_space(3)))
; template <bool LOCAL>
; __device__ __forceinline__ void attn_unit(const bf16_t* Q, const bf16_t* KT, const bf16_t* VT, bf16_t* O, LAS unsigned char* lds, int b, int h, int r, int w, int tq, int lane) {
;     const int g = lane >> 4, q = lane & 15;
;     const int qrow = LOCAL ? (b * SEQ + r * GRID_W + 16 * w + q) : (ML + b * CTX + 16 * tq + q);
;     bf16x8 bq[4];
;     { const bf16_t* qp = Q + (size_t)qrow * D + h * HD + 8 * g;
; #pragma unroll
;       for (int ks = 0; ks < 4; ++ks) bq[ks] = *(const bf16x8*)(qp + 32 * ks); }
;     constexpr int NP = LOCAL ? 16 : 8, CP = LOCAL ? 8 : 0;
;     f32x4 s[2 * NP];
;     int rs = 0, ws = 0;
;     if (LOCAL) { rs = r - 4; rs = rs < 0 ? 0 : (rs > 24 ? 24 : rs); ws = 16 * w - 8; ws = ws < 0 ? 0 : (ws > 32 ? 32 : ws); }
;     const int rgl = b * SEQ + rs * GRID_W + ws;
;     if (LOCAL) {
;         const bf16_t* kloc = KT + ((size_t)(((rgl >> 3) + (q >> 2)) * NH + h)) * 1024 + (q & 3) * 32 + g * 8;
;         bf16x8 ka[2][8];
;     ...
;         ATT_KLOAD(0, 0);
; #pragma unroll
;         for (int p = 0; p < 8; ++p) {
;             __builtin_amdgcn_s_barrier();
;             if (p + 1 < 8) ATT_KLOAD((p + 1) & 1, p + 1);
;             __builtin_amdgcn_sched_barrier(0);
; #pragma unroll
;             for (int f = 0; f < 2; ++f) { f32x4 a = {0.f, 0.f, 0.f, 0.f};
; #pragma unroll
;                 for (int ks = 0; ks < 4; ++ks) a = __builtin_amdgcn_mfma_f32_16x16x32_bf16(ka[p & 1][f * 4 + ks], bq[ks], a, 0, 0, 0);
;                 s[2 * p + f] = a; }
;             __builtin_amdgcn_sched_barrier(0);
;         }
;     ...
;     {
;         const LAS unsigned char* vl = lds + 65536 + g * 2048 + q * 16;
; #pragma unroll
;         for (int p = 0; p < 8; ++p)
; #pragma unroll
;             for (int df = 0; df < 8; ++df) o[df] = __builtin_amdgcn_mfma_f32_16x16x32_bf16(*(const LAS bf16x8*)(vl + p * 8192 + df * 256), pb[CP + p], o[df], 0, 0, 0);
;     }
;     const float inv = 1.f / sum;
;     bf16_t* op = O + (size_t)qrow * D + h * HD + 4 * g;
; #pragma unroll
;     for (int df = 0; df < 8; ++df) { u32x2 wv; wv.x = cvt_pk_bf16(o[df][0] * inv, o[df][1] * inv); wv.y = cvt_pk_bf16(o[df][2] * inv, o[df][3] * inv); *(u32x2*)(op + 16 * df) = wv; }
	v_mfma_f32_16x16x32_bf16 v[2:5], v[246:249], v[18:21], v[2:5]
	s_nop 7
	v_add_f32_e32 v18, v134, v135
	v_div_scale_f32 v19, s[4:5], v18, v18, 1.0
	v_rcp_f32_e32 v20, v19
	s_nop 0
	v_fma_f32 v21, -v19, v20, 1.0
	v_fmac_f32_e32 v20, v21, v20
	v_div_scale_f32 v21, vcc, 1.0, v18, 1.0
	v_mul_f32_e32 v38, v21, v20
	v_fma_f32 v39, -v19, v38, v21
	v_fmac_f32_e32 v38, v39, v20
	v_fma_f32 v19, -v19, v38, v21
	v_div_fmas_f32 v19, v19, v20, v38
	v_div_fixup_f32 v20, v19, v18, 1.0
	v_mul_f32_e32 v6, v20, v6
	v_mul_f32_e32 v7, v20, v7
	v_cvt_pk_bf16_f32 v6, v6, v7
	v_mul_f32_e32 v7, v20, v8
	v_lshl_add_u64 v[18:19], v[130:131], 1, v[160:161]
	v_mul_f32_e32 v8, v20, v9
	v_cvt_pk_bf16_f32 v7, v7, v8
	global_store_dwordx2 v[18:19], v[6:7], off
	v_mul_f32_e32 v6, v20, v10
	v_mul_f32_e32 v7, v20, v11
	v_cvt_pk_bf16_f32 v6, v6, v7
	v_mul_f32_e32 v7, v20, v12
	v_mul_f32_e32 v8, v20, v13
	v_cvt_pk_bf16_f32 v7, v7, v8
	global_store_dwordx2 v[18:19], v[6:7], off offset:32
	v_mul_f32_e32 v6, v20, v14
	v_mul_f32_e32 v7, v20, v15
	v_cvt_pk_bf16_f32 v6, v6, v7
	v_mul_f32_e32 v7, v20, v16
	v_mul_f32_e32 v8, v20, v17
	v_cvt_pk_bf16_f32 v7, v7, v8
	global_store_dwordx2 v[18:19], v[6:7], off offset:64
	v_mul_f32_e32 v6, v20, v22
	v_mul_f32_e32 v7, v20, v23
	v_cvt_pk_bf16_f32 v6, v6, v7
	v_mul_f32_e32 v7, v20, v24
	v_mul_f32_e32 v8, v20, v25
	v_cvt_pk_bf16_f32 v7, v7, v8
	global_store_dwordx2 v[18:19], v[6:7], off offset:96
	v_mul_f32_e32 v6, v20, v26
	v_mul_f32_e32 v7, v20, v27
	v_cvt_pk_bf16_f32 v6, v6, v7
	v_mul_f32_e32 v7, v20, v28
	v_mul_f32_e32 v8, v20, v29
	v_cvt_pk_bf16_f32 v7, v7, v8
	global_store_dwordx2 v[18:19], v[6:7], off offset:128
	v_mul_f32_e32 v6, v20, v30
	v_mul_f32_e32 v7, v20, v31
	v_cvt_pk_bf16_f32 v6, v6, v7
	v_mul_f32_e32 v7, v20, v32
	v_mul_f32_e32 v8, v20, v33
	v_cvt_pk_bf16_f32 v7, v7, v8
	global_store_dwordx2 v[18:19], v[6:7], off offset:160
	v_mul_f32_e32 v6, v20, v34
	v_mul_f32_e32 v7, v20, v35
	v_cvt_pk_bf16_f32 v6, v6, v7
	v_mul_f32_e32 v7, v20, v36
	v_mul_f32_e32 v2, v20, v2
	v_mul_f32_e32 v3, v20, v3
	v_mul_f32_e32 v8, v20, v37
	v_cvt_pk_bf16_f32 v7, v7, v8
	global_store_dwordx2 v[18:19], v[6:7], off offset:192
	v_cvt_pk_bf16_f32 v2, v2, v3
	v_mul_f32_e32 v3, v20, v4
	v_mul_f32_e32 v4, v20, v5
	v_cvt_pk_bf16_f32 v3, v3, v4
	global_store_dwordx2 v[18:19], v[2:3], off offset:224
	s_cbranch_scc1 .LBB9_802
.LBB9_674:
	v_ashrrev_i32_e32 v163, 31, v162
	v_lshlrev_b64 v[2:3], 12, v[162:163]
	s_add_i32 s4, s50, s48
	v_lshl_add_u64 v[2:3], v[158:159], 0, v[2:3]
	global_load_dwordx4 v[138:141], v[2:3], off
	global_load_dwordx4 v[134:137], v[2:3], off offset:64
	global_load_dwordx4 v[130:133], v[2:3], off offset:128
	global_load_dwordx4 v[62:65], v[2:3], off offset:192
	v_med3_i32 v2, s4, 4, 28
	v_lshlrev_b32_e32 v2, 6, v2
	v_add_u32_e32 v2, v2, v157
	v_add_u32_e32 v2, 0xffffff00, v2
	v_ashrrev_i32_e32 v194, 3, v2
	v_add_u32_e32 v2, v194, v168
	v_lshl_or_b32 v2, v2, 4, s72
	v_ashrrev_i32_e32 v3, 31, v2
	v_lshlrev_b64 v[2:3], 11, v[2:3]
	v_lshl_add_u64 v[70:71], v[146:147], 0, v[2:3]
	v_add_co_u32_e32 v66, vcc, s6, v70
	global_load_dwordx4 v[2:5], v[70:71], off
	global_load_dwordx4 v[6:9], v[70:71], off offset:256
	global_load_dwordx4 v[10:13], v[70:71], off offset:512
	global_load_dwordx4 v[14:17], v[70:71], off offset:768
	global_load_dwordx4 v[18:21], v[70:71], off offset:1024
	global_load_dwordx4 v[22:25], v[70:71], off offset:1280
	global_load_dwordx4 v[26:29], v[70:71], off offset:1536
	global_load_dwordx4 v[30:33], v[70:71], off offset:1792
	v_addc_co_u32_e32 v67, vcc, 0, v71, vcc
	s_barrier
	global_load_dwordx4 v[34:37], v[66:67], off
	global_load_dwordx4 v[38:41], v[66:67], off offset:256
	global_load_dwordx4 v[42:45], v[66:67], off offset:512
	global_load_dwordx4 v[46:49], v[66:67], off offset:768
	global_load_dwordx4 v[50:53], v[66:67], off offset:1024
	global_load_dwordx4 v[54:57], v[66:67], off offset:1280
	global_load_dwordx4 v[58:61], v[66:67], off offset:1536
	s_nop 0
	global_load_dwordx4 v[66:69], v[66:67], off offset:1792
	v_med3_i32 v72, s52, 4, 28
	v_add_u32_e32 v195, s51, v72
	s_waitcnt vmcnt(15)
	v_mfma_f32_16x16x32_bf16 v[2:5], v[2:5], v[138:141], 0
	s_waitcnt vmcnt(13)
	v_mfma_f32_16x16x32_bf16 v[2:5], v[10:13], v[134:137], v[2:5]
	s_waitcnt vmcnt(11)
	v_mfma_f32_16x16x32_bf16 v[2:5], v[18:21], v[130:133], v[2:5]
	s_waitcnt vmcnt(9)
	v_mfma_f32_16x16x32_bf16 v[126:129], v[26:29], v[62:65], v[2:5]
	v_mfma_f32_16x16x32_bf16 v[2:5], v[6:9], v[138:141], 0
	v_mfma_f32_16x16x32_bf16 v[2:5], v[14:17], v[134:137], v[2:5]
	v_mfma_f32_16x16x32_bf16 v[2:5], v[22:25], v[130:133], v[2:5]
	s_waitcnt vmcnt(8)
	v_mfma_f32_16x16x32_bf16 v[122:125], v[30:33], v[62:65], v[2:5]
	v_add_co_u32_e32 v30, vcc, s7, v70
	s_barrier
	s_nop 0
	v_addc_co_u32_e32 v31, vcc, 0, v71, vcc
	s_nop 1
	global_load_dwordx4 v[2:5], v[30:31], off
	global_load_dwordx4 v[6:9], v[30:31], off offset:256
	global_load_dwordx4 v[10:13], v[30:31], off offset:512
	global_load_dwordx4 v[14:17], v[30:31], off offset:768
	global_load_dwordx4 v[18:21], v[30:31], off offset:1024
	global_load_dwordx4 v[22:25], v[30:31], off offset:1280
	global_load_dwordx4 v[26:29], v[30:31], off offset:1536
	s_nop 0
	global_load_dwordx4 v[30:33], v[30:31], off offset:1792
	s_waitcnt vmcnt(15)
	v_mfma_f32_16x16x32_bf16 v[34:37], v[34:37], v[138:141], 0
	s_waitcnt vmcnt(13)
	v_mfma_f32_16x16x32_bf16 v[34:37], v[42:45], v[134:137], v[34:37]
	s_waitcnt vmcnt(11)
	v_mfma_f32_16x16x32_bf16 v[34:37], v[50:53], v[130:133], v[34:37]
	s_waitcnt vmcnt(9)
	v_mfma_f32_16x16x32_bf16 v[118:121], v[58:61], v[62:65], v[34:37]
	v_mfma_f32_16x16x32_bf16 v[34:37], v[38:41], v[138:141], 0
	v_mfma_f32_16x16x32_bf16 v[34:37], v[46:49], v[134:137], v[34:37]
	v_mfma_f32_16x16x32_bf16 v[34:37], v[54:57], v[130:133], v[34:37]
	s_waitcnt vmcnt(8)
	v_mfma_f32_16x16x32_bf16 v[114:117], v[66:69], v[62:65], v[34:37]
	v_add_co_u32_e32 v66, vcc, s2, v70
	s_barrier
; #define ATT_KLOAD(buf, p) do { const bf16_t* kp_ = kloc + (size_t)((p) * 8 * NH) * 1024; \
;         _Pragma("unroll") for (int f = 0; f < 2; ++f) _Pragma("unroll") for (int ks = 0; ks < 4; ++ks) ka[buf][f * 4 + ks] = *(const bf16x8*)(kp_ + f * 128 + ks * 256); } while (0)
; template <bool LOCAL>
; __device__ __forceinline__ void attn_unit(const bf16_t* Q, const bf16_t* KT, const bf16_t* VT, bf16_t* O, LAS unsigned char* lds, int b, int h, int r, int w, int tq, int lane) {
;     ...
;     if (LOCAL) {
;         const bf16_t* kloc = KT + ((size_t)(((rgl >> 3) + (q >> 2)) * NH + h)) * 1024 + (q & 3) * 32 + g * 8;
;         bf16x8 ka[2][8];
;     ...
;         ATT_KLOAD(0, 0);
; #pragma unroll
;         for (int p = 0; p < 8; ++p) {
;             __builtin_amdgcn_s_barrier();
;             if (p + 1 < 8) ATT_KLOAD((p + 1) & 1, p + 1);
;             __builtin_amdgcn_sched_barrier(0);
; #pragma unroll
;             for (int f = 0; f < 2; ++f) { f32x4 a = {0.f, 0.f, 0.f, 0.f};
; #pragma unroll
;                 for (int ks = 0; ks < 4; ++ks) a = __builtin_amdgcn_mfma_f32_16x16x32_bf16(ka[p & 1][f * 4 + ks], bq[ks], a, 0, 0, 0);
;                 s[2 * p + f] = a; }
;             __builtin_amdgcn_sched_barrier(0);
;         }
	s_nop 0
	v_addc_co_u32_e32 v67, vcc, 0, v71, vcc
	s_nop 1
	global_load_dwordx4 v[34:37], v[66:67], off
	global_load_dwordx4 v[38:41], v[66:67], off offset:256
	global_load_dwordx4 v[42:45], v[66:67], off offset:512
	global_load_dwordx4 v[46:49], v[66:67], off offset:768
	global_load_dwordx4 v[50:53], v[66:67], off offset:1024
	global_load_dwordx4 v[54:57], v[66:67], off offset:1280
	global_load_dwordx4 v[58:61], v[66:67], off offset:1536
	s_nop 0
	global_load_dwordx4 v[66:69], v[66:67], off offset:1792
	s_waitcnt vmcnt(15)
	v_mfma_f32_16x16x32_bf16 v[2:5], v[2:5], v[138:141], 0
	s_waitcnt vmcnt(13)
	v_mfma_f32_16x16x32_bf16 v[2:5], v[10:13], v[134:137], v[2:5]
	s_waitcnt vmcnt(11)
	v_mfma_f32_16x16x32_bf16 v[2:5], v[18:21], v[130:133], v[2:5]
	s_waitcnt vmcnt(9)
	v_mfma_f32_16x16x32_bf16 v[110:113], v[26:29], v[62:65], v[2:5]
	v_mfma_f32_16x16x32_bf16 v[2:5], v[6:9], v[138:141], 0
	v_mfma_f32_16x16x32_bf16 v[2:5], v[14:17], v[134:137], v[2:5]
	v_mfma_f32_16x16x32_bf16 v[2:5], v[22:25], v[130:133], v[2:5]
	s_waitcnt vmcnt(8)
	v_mfma_f32_16x16x32_bf16 v[106:109], v[30:33], v[62:65], v[2:5]
	v_add_co_u32_e32 v30, vcc, s60, v70
	s_barrier
	s_nop 0
	v_addc_co_u32_e32 v31, vcc, 0, v71, vcc
	s_nop 1
	global_load_dwordx4 v[2:5], v[30:31], off
	global_load_dwordx4 v[6:9], v[30:31], off offset:256
	global_load_dwordx4 v[10:13], v[30:31], off offset:512
	global_load_dwordx4 v[14:17], v[30:31], off offset:768
	global_load_dwordx4 v[18:21], v[30:31], off offset:1024
	global_load_dwordx4 v[22:25], v[30:31], off offset:1280
	global_load_dwordx4 v[26:29], v[30:31], off offset:1536
	s_nop 0
	global_load_dwordx4 v[30:33], v[30:31], off offset:1792
	s_waitcnt vmcnt(15)
	v_mfma_f32_16x16x32_bf16 v[34:37], v[34:37], v[138:141], 0
	s_waitcnt vmcnt(13)
	v_mfma_f32_16x16x32_bf16 v[34:37], v[42:45], v[134:137], v[34:37]
	s_waitcnt vmcnt(11)
	v_mfma_f32_16x16x32_bf16 v[34:37], v[50:53], v[130:133], v[34:37]
	s_waitcnt vmcnt(9)
	v_mfma_f32_16x16x32_bf16 v[102:105], v[58:61], v[62:65], v[34:37]
	v_mfma_f32_16x16x32_bf16 v[34:37], v[38:41], v[138:141], 0
	v_mfma_f32_16x16x32_bf16 v[34:37], v[46:49], v[134:137], v[34:37]
	v_mfma_f32_16x16x32_bf16 v[34:37], v[54:57], v[130:133], v[34:37]
	s_waitcnt vmcnt(8)
	v_mfma_f32_16x16x32_bf16 v[98:101], v[66:69], v[62:65], v[34:37]
	v_add_co_u32_e32 v66, vcc, s61, v70
	s_barrier
	s_nop 0
	v_addc_co_u32_e32 v67, vcc, 0, v71, vcc
	s_nop 1
	global_load_dwordx4 v[34:37], v[66:67], off
	global_load_dwordx4 v[38:41], v[66:67], off offset:256
	global_load_dwordx4 v[42:45], v[66:67], off offset:512
	global_load_dwordx4 v[46:49], v[66:67], off offset:768
	global_load_dwordx4 v[50:53], v[66:67], off offset:1024
	global_load_dwordx4 v[54:57], v[66:67], off offset:1280
	global_load_dwordx4 v[58:61], v[66:67], off offset:1536
	s_nop 0
	global_load_dwordx4 v[66:69], v[66:67], off offset:1792
	s_waitcnt vmcnt(15)
	v_mfma_f32_16x16x32_bf16 v[2:5], v[2:5], v[138:141], 0
	s_waitcnt vmcnt(13)
	v_mfma_f32_16x16x32_bf16 v[2:5], v[10:13], v[134:137], v[2:5]
	s_waitcnt vmcnt(11)
	v_mfma_f32_16x16x32_bf16 v[2:5], v[18:21], v[130:133], v[2:5]
	s_waitcnt vmcnt(9)
	v_mfma_f32_16x16x32_bf16 v[94:97], v[26:29], v[62:65], v[2:5]
	v_mfma_f32_16x16x32_bf16 v[2:5], v[6:9], v[138:141], 0
	v_mfma_f32_16x16x32_bf16 v[2:5], v[14:17], v[134:137], v[2:5]
	v_mfma_f32_16x16x32_bf16 v[2:5], v[22:25], v[130:133], v[2:5]
	s_waitcnt vmcnt(8)
	v_mfma_f32_16x16x32_bf16 v[90:93], v[30:33], v[62:65], v[2:5]
	v_add_co_u32_e32 v30, vcc, s17, v70
	s_barrier
	s_nop 0
	v_addc_co_u32_e32 v31, vcc, 0, v71, vcc
	s_nop 1
	global_load_dwordx4 v[2:5], v[30:31], off
	global_load_dwordx4 v[6:9], v[30:31], off offset:256
	global_load_dwordx4 v[10:13], v[30:31], off offset:512
	global_load_dwordx4 v[14:17], v[30:31], off offset:768
	global_load_dwordx4 v[18:21], v[30:31], off offset:1024
	global_load_dwordx4 v[22:25], v[30:31], off offset:1280
	global_load_dwordx4 v[26:29], v[30:31], off offset:1536
	s_nop 0
	global_load_dwordx4 v[30:33], v[30:31], off offset:1792
	s_waitcnt vmcnt(15)
	v_mfma_f32_16x16x32_bf16 v[34:37], v[34:37], v[138:141], 0
	s_waitcnt vmcnt(13)
	v_mfma_f32_16x16x32_bf16 v[34:37], v[42:45], v[134:137], v[34:37]
	s_waitcnt vmcnt(11)
	v_mfma_f32_16x16x32_bf16 v[34:37], v[50:53], v[130:133], v[34:37]
	s_waitcnt vmcnt(9)
	v_mfma_f32_16x16x32_bf16 v[86:89], v[58:61], v[62:65], v[34:37]
	v_mfma_f32_16x16x32_bf16 v[34:37], v[38:41], v[138:141], 0
	v_mfma_f32_16x16x32_bf16 v[34:37], v[46:49], v[134:137], v[34:37]
	v_mfma_f32_16x16x32_bf16 v[34:37], v[54:57], v[130:133], v[34:37]
	s_waitcnt vmcnt(8)
	v_mfma_f32_16x16x32_bf16 v[82:85], v[66:69], v[62:65], v[34:37]
	v_add_co_u32_e32 v66, vcc, s62, v70
	s_barrier
	s_nop 0
	v_addc_co_u32_e32 v67, vcc, 0, v71, vcc
	s_nop 1
	global_load_dwordx4 v[34:37], v[66:67], off
	global_load_dwordx4 v[38:41], v[66:67], off offset:256
	global_load_dwordx4 v[42:45], v[66:67], off offset:512
	global_load_dwordx4 v[46:49], v[66:67], off offset:768
	global_load_dwordx4 v[50:53], v[66:67], off offset:1024
	global_load_dwordx4 v[54:57], v[66:67], off offset:1280
	global_load_dwordx4 v[58:61], v[66:67], off offset:1536
	s_nop 0
	global_load_dwordx4 v[66:69], v[66:67], off offset:1792
	s_waitcnt vmcnt(15)
	v_mfma_f32_16x16x32_bf16 v[2:5], v[2:5], v[138:141], 0
	s_waitcnt vmcnt(13)
	v_mfma_f32_16x16x32_bf16 v[2:5], v[10:13], v[134:137], v[2:5]
	s_waitcnt vmcnt(11)
	v_mfma_f32_16x16x32_bf16 v[2:5], v[18:21], v[130:133], v[2:5]
	s_waitcnt vmcnt(9)
	v_mfma_f32_16x16x32_bf16 v[78:81], v[26:29], v[62:65], v[2:5]
	v_mfma_f32_16x16x32_bf16 v[2:5], v[6:9], v[138:141], 0
	v_mfma_f32_16x16x32_bf16 v[2:5], v[14:17], v[134:137], v[2:5]
	v_mfma_f32_16x16x32_bf16 v[2:5], v[22:25], v[130:133], v[2:5]
	s_waitcnt vmcnt(8)
	v_mfma_f32_16x16x32_bf16 v[74:77], v[30:33], v[62:65], v[2:5]
	s_barrier
; #define LAS __attribute__((address_space(3)))
; template <bool LOCAL>
; __device__ __forceinline__ void attn_unit(const bf16_t* Q, const bf16_t* KT, const bf16_t* VT, bf16_t* O, LAS unsigned char* lds, int b, int h, int r, int w, int tq, int lane) {
;     ...
; #pragma unroll
;             for (int f = 0; f < 2; ++f) { f32x4 a = {0.f, 0.f, 0.f, 0.f};
; #pragma unroll
;                 for (int ks = 0; ks < 4; ++ks) a = __builtin_amdgcn_mfma_f32_16x16x32_bf16(ka[p & 1][f * 4 + ks], bq[ks], a, 0, 0, 0);
;                 s[2 * p + f] = a; }
;             __builtin_amdgcn_sched_barrier(0);
;         }
;     ...
;     }
;     {
;         const LAS unsigned char* kl = lds + (q >> 2) * 2048 + (((q & 3) * 4 + g) ^ ((q >> 2) & 2)) * 16;
; #pragma unroll
;         for (int p = 0; p < 8; ++p)
; #pragma unroll
;             for (int f = 0; f < 2; ++f) { f32x4 a = {0.f, 0.f, 0.f, 0.f};
; #pragma unroll
;                 for (int ks = 0; ks < 4; ++ks) a = __builtin_amdgcn_mfma_f32_16x16x32_bf16(*(const LAS bf16x8*)(kl + p * 8192 + ks * 512 + f * 256), bq[ks], a, 0, 0, 0);
;                 s[2 * (CP + p) + f] = a; }
;     }
	s_waitcnt vmcnt(7)
	v_mfma_f32_16x16x32_bf16 v[2:5], v[34:37], v[138:141], 0
	s_waitcnt vmcnt(5)
	v_mfma_f32_16x16x32_bf16 v[2:5], v[42:45], v[134:137], v[2:5]
	s_waitcnt vmcnt(3)
	v_mfma_f32_16x16x32_bf16 v[2:5], v[50:53], v[130:133], v[2:5]
	s_waitcnt vmcnt(1)
	v_mfma_f32_16x16x32_bf16 v[70:73], v[58:61], v[62:65], v[2:5]
	v_mfma_f32_16x16x32_bf16 v[2:5], v[38:41], v[138:141], 0
	v_mfma_f32_16x16x32_bf16 v[2:5], v[46:49], v[134:137], v[2:5]
	v_mfma_f32_16x16x32_bf16 v[2:5], v[54:57], v[130:133], v[2:5]
	s_waitcnt vmcnt(0)
	v_mfma_f32_16x16x32_bf16 v[66:69], v[66:69], v[62:65], v[2:5]
	s_nop 5
	s_waitcnt lgkmcnt(0)
	s_movk_i32 s4, 0x7c
	ds_read_b128 v[208:211], v169
	ds_read_b128 v[212:215], v169 offset:512
	ds_read_b128 v[216:219], v169 offset:1024
	ds_read_b128 v[220:223], v169 offset:1536
	ds_read_b128 v[224:227], v169 offset:256
	ds_read_b128 v[228:231], v169 offset:768
	ds_read_b128 v[232:235], v169 offset:1280
	ds_read_b128 v[246:249], v169 offset:1792
	s_waitcnt lgkmcnt(7)
	v_mfma_f32_16x16x32_bf16 v[2:5], v[208:211], v[138:141], 0
	ds_read_b128 v[208:211], v169 offset:8192
	s_waitcnt lgkmcnt(7)
	v_mfma_f32_16x16x32_bf16 v[2:5], v[212:215], v[134:137], v[2:5]
	ds_read_b128 v[212:215], v169 offset:8704
	s_waitcnt lgkmcnt(7)
	v_mfma_f32_16x16x32_bf16 v[2:5], v[216:219], v[130:133], v[2:5]
	ds_read_b128 v[216:219], v169 offset:9216
	s_waitcnt lgkmcnt(7)
	v_mfma_f32_16x16x32_bf16 v[2:5], v[220:223], v[62:65], v[2:5]
	ds_read_b128 v[220:223], v169 offset:9728
	s_waitcnt lgkmcnt(7)
	v_mfma_f32_16x16x32_bf16 v[6:9], v[224:227], v[138:141], 0
	ds_read_b128 v[224:227], v169 offset:8448
	s_waitcnt lgkmcnt(7)
	v_mfma_f32_16x16x32_bf16 v[6:9], v[228:231], v[134:137], v[6:9]
	ds_read_b128 v[228:231], v169 offset:8960
	s_waitcnt lgkmcnt(7)
	v_mfma_f32_16x16x32_bf16 v[6:9], v[232:235], v[130:133], v[6:9]
	ds_read_b128 v[232:235], v169 offset:9472
	s_waitcnt lgkmcnt(7)
	v_mfma_f32_16x16x32_bf16 v[10:13], v[246:249], v[62:65], v[6:9]
	ds_read_b128 v[246:249], v169 offset:9984
	s_waitcnt lgkmcnt(7)
	v_mfma_f32_16x16x32_bf16 v[6:9], v[208:211], v[138:141], 0
	ds_read_b128 v[208:211], v169 offset:16384
	s_waitcnt lgkmcnt(7)
	v_mfma_f32_16x16x32_bf16 v[6:9], v[212:215], v[134:137], v[6:9]
	ds_read_b128 v[212:215], v169 offset:16896
	s_waitcnt lgkmcnt(7)
	v_mfma_f32_16x16x32_bf16 v[6:9], v[216:219], v[130:133], v[6:9]
	ds_read_b128 v[216:219], v169 offset:17408
	s_waitcnt lgkmcnt(7)
	v_mfma_f32_16x16x32_bf16 v[6:9], v[220:223], v[62:65], v[6:9]
	ds_read_b128 v[220:223], v169 offset:17920
	s_waitcnt lgkmcnt(7)
	v_mfma_f32_16x16x32_bf16 v[14:17], v[224:227], v[138:141], 0
	ds_read_b128 v[224:227], v169 offset:16640
	s_waitcnt lgkmcnt(7)
	v_mfma_f32_16x16x32_bf16 v[14:17], v[228:231], v[134:137], v[14:17]
	ds_read_b128 v[228:231], v169 offset:17152
	s_waitcnt lgkmcnt(7)
	v_mfma_f32_16x16x32_bf16 v[14:17], v[232:235], v[130:133], v[14:17]
	ds_read_b128 v[232:235], v169 offset:17664
	s_waitcnt lgkmcnt(7)
	v_mfma_f32_16x16x32_bf16 v[18:21], v[246:249], v[62:65], v[14:17]
	ds_read_b128 v[246:249], v169 offset:18176
	s_waitcnt lgkmcnt(7)
	v_mfma_f32_16x16x32_bf16 v[14:17], v[208:211], v[138:141], 0
	ds_read_b128 v[208:211], v169 offset:24576
	s_waitcnt lgkmcnt(7)
	v_mfma_f32_16x16x32_bf16 v[14:17], v[212:215], v[134:137], v[14:17]
	ds_read_b128 v[212:215], v169 offset:25088
	s_waitcnt lgkmcnt(7)
	v_mfma_f32_16x16x32_bf16 v[14:17], v[216:219], v[130:133], v[14:17]
	ds_read_b128 v[216:219], v169 offset:25600
	s_waitcnt lgkmcnt(7)
	v_mfma_f32_16x16x32_bf16 v[14:17], v[220:223], v[62:65], v[14:17]
	ds_read_b128 v[220:223], v169 offset:26112
	s_waitcnt lgkmcnt(7)
	v_mfma_f32_16x16x32_bf16 v[22:25], v[224:227], v[138:141], 0
	ds_read_b128 v[224:227], v169 offset:24832
	s_waitcnt lgkmcnt(7)
	v_mfma_f32_16x16x32_bf16 v[22:25], v[228:231], v[134:137], v[22:25]
	ds_read_b128 v[228:231], v169 offset:25344
	s_waitcnt lgkmcnt(7)
	v_mfma_f32_16x16x32_bf16 v[22:25], v[232:235], v[130:133], v[22:25]
	ds_read_b128 v[232:235], v169 offset:25856
	s_waitcnt lgkmcnt(7)
	v_mfma_f32_16x16x32_bf16 v[26:29], v[246:249], v[62:65], v[22:25]
	ds_read_b128 v[246:249], v169 offset:26368
	s_waitcnt lgkmcnt(7)
	v_mfma_f32_16x16x32_bf16 v[22:25], v[208:211], v[138:141], 0
	ds_read_b128 v[208:211], v169 offset:32768
	s_waitcnt lgkmcnt(7)
	v_mfma_f32_16x16x32_bf16 v[22:25], v[212:215], v[134:137], v[22:25]
	ds_read_b128 v[212:215], v169 offset:33280
	s_waitcnt lgkmcnt(7)
	v_mfma_f32_16x16x32_bf16 v[22:25], v[216:219], v[130:133], v[22:25]
	ds_read_b128 v[216:219], v169 offset:33792
	s_waitcnt lgkmcnt(7)
	v_mfma_f32_16x16x32_bf16 v[22:25], v[220:223], v[62:65], v[22:25]
	ds_read_b128 v[220:223], v169 offset:34304
	s_waitcnt lgkmcnt(7)
; #define LAS __attribute__((address_space(3)))
; template <bool LOCAL>
; __device__ __forceinline__ void attn_unit(const bf16_t* Q, const bf16_t* KT, const bf16_t* VT, bf16_t* O, LAS unsigned char* lds, int b, int h, int r, int w, int tq, int lane) {
;     ...
;     {
;         const LAS unsigned char* kl = lds + (q >> 2) * 2048 + (((q & 3) * 4 + g) ^ ((q >> 2) & 2)) * 16;
; #pragma unroll
;         for (int p = 0; p < 8; ++p)
; #pragma unroll
;             for (int f = 0; f < 2; ++f) { f32x4 a = {0.f, 0.f, 0.f, 0.f};
; #pragma unroll
;                 for (int ks = 0; ks < 4; ++ks) a = __builtin_amdgcn_mfma_f32_16x16x32_bf16(*(const LAS bf16x8*)(kl + p * 8192 + ks * 512 + f * 256), bq[ks], a, 0, 0, 0);
;                 s[2 * (CP + p) + f] = a; }
;     }
;     if (LOCAL) {
;         const int c = 16 * w + q; int cs = c - 8; cs = cs < 0 ? 0 : (cs > 48 ? 48 : cs);
;         const LAS float* rp = (const LAS float*)(lds + LDS_MISC + 1024);
; #pragma unroll
;         for (int p = 0; p < 8; ++p) { const int ro = (rs + p - r + 7) * 31;
; #pragma unroll
;             for (int f = 0; f < 2; ++f)
; #pragma unroll
;                 for (int j = 0; j < 4; ++j) { const int kc = ws + 8 * g + 4 * f + j; const bool valid = (kc >= cs) && (kc < cs + 16);
;                     int rel = kc - c + 15; rel = rel < 0 ? 0 : (rel > 30 ? 30 : rel);
;                     const float bias = rp[ro + rel];
;                     s[p * 2 + f][j] = valid ? s[p * 2 + f][j] + bias : -INFINITY; } }
	v_mfma_f32_16x16x32_bf16 v[30:33], v[224:227], v[138:141], 0
	ds_read_b128 v[224:227], v169 offset:33024
	s_waitcnt lgkmcnt(7)
	v_mfma_f32_16x16x32_bf16 v[30:33], v[228:231], v[134:137], v[30:33]
	ds_read_b128 v[228:231], v169 offset:33536
	s_waitcnt lgkmcnt(7)
	v_mfma_f32_16x16x32_bf16 v[30:33], v[232:235], v[130:133], v[30:33]
	ds_read_b128 v[232:235], v169 offset:34048
	s_waitcnt lgkmcnt(7)
	v_mfma_f32_16x16x32_bf16 v[34:37], v[246:249], v[62:65], v[30:33]
	ds_read_b128 v[246:249], v169 offset:34560
	s_waitcnt lgkmcnt(7)
	v_mfma_f32_16x16x32_bf16 v[30:33], v[208:211], v[138:141], 0
	ds_read_b128 v[208:211], v169 offset:40960
	s_waitcnt lgkmcnt(7)
	v_mfma_f32_16x16x32_bf16 v[30:33], v[212:215], v[134:137], v[30:33]
	ds_read_b128 v[212:215], v169 offset:41472
	s_waitcnt lgkmcnt(7)
	v_mfma_f32_16x16x32_bf16 v[30:33], v[216:219], v[130:133], v[30:33]
	ds_read_b128 v[216:219], v169 offset:41984
	s_waitcnt lgkmcnt(7)
	v_mfma_f32_16x16x32_bf16 v[30:33], v[220:223], v[62:65], v[30:33]
	ds_read_b128 v[220:223], v169 offset:42496
	s_waitcnt lgkmcnt(7)
	v_mfma_f32_16x16x32_bf16 v[38:41], v[224:227], v[138:141], 0
	ds_read_b128 v[224:227], v169 offset:41216
	s_waitcnt lgkmcnt(7)
	v_mfma_f32_16x16x32_bf16 v[38:41], v[228:231], v[134:137], v[38:41]
	ds_read_b128 v[228:231], v169 offset:41728
	s_waitcnt lgkmcnt(7)
	v_mfma_f32_16x16x32_bf16 v[38:41], v[232:235], v[130:133], v[38:41]
	ds_read_b128 v[232:235], v169 offset:42240
	s_waitcnt lgkmcnt(7)
	v_mfma_f32_16x16x32_bf16 v[42:45], v[246:249], v[62:65], v[38:41]
	ds_read_b128 v[246:249], v169 offset:42752
	s_waitcnt lgkmcnt(7)
	v_mfma_f32_16x16x32_bf16 v[38:41], v[208:211], v[138:141], 0
	ds_read_b128 v[208:211], v169 offset:49152
	s_waitcnt lgkmcnt(7)
	v_mfma_f32_16x16x32_bf16 v[38:41], v[212:215], v[134:137], v[38:41]
	ds_read_b128 v[212:215], v169 offset:49664
	s_waitcnt lgkmcnt(7)
	v_mfma_f32_16x16x32_bf16 v[38:41], v[216:219], v[130:133], v[38:41]
	ds_read_b128 v[216:219], v169 offset:50176
	s_waitcnt lgkmcnt(7)
	v_mfma_f32_16x16x32_bf16 v[38:41], v[220:223], v[62:65], v[38:41]
	ds_read_b128 v[220:223], v169 offset:50688
	s_waitcnt lgkmcnt(7)
	v_mfma_f32_16x16x32_bf16 v[46:49], v[224:227], v[138:141], 0
	ds_read_b128 v[224:227], v169 offset:49408
	s_waitcnt lgkmcnt(7)
	v_mfma_f32_16x16x32_bf16 v[46:49], v[228:231], v[134:137], v[46:49]
	ds_read_b128 v[228:231], v169 offset:49920
	s_waitcnt lgkmcnt(7)
	v_mfma_f32_16x16x32_bf16 v[46:49], v[232:235], v[130:133], v[46:49]
	ds_read_b128 v[232:235], v169 offset:50432
	s_waitcnt lgkmcnt(7)
	v_mfma_f32_16x16x32_bf16 v[50:53], v[246:249], v[62:65], v[46:49]
	ds_read_b128 v[246:249], v169 offset:50944
	s_waitcnt lgkmcnt(7)
	v_mfma_f32_16x16x32_bf16 v[46:49], v[208:211], v[138:141], 0
	ds_read_b128 v[208:211], v169 offset:57344
	s_waitcnt lgkmcnt(7)
	v_mfma_f32_16x16x32_bf16 v[46:49], v[212:215], v[134:137], v[46:49]
	ds_read_b128 v[212:215], v169 offset:57856
	s_waitcnt lgkmcnt(7)
	v_mfma_f32_16x16x32_bf16 v[46:49], v[216:219], v[130:133], v[46:49]
	ds_read_b128 v[216:219], v169 offset:58368
	s_waitcnt lgkmcnt(7)
	v_mfma_f32_16x16x32_bf16 v[46:49], v[220:223], v[62:65], v[46:49]
	ds_read_b128 v[220:223], v169 offset:58880
	s_waitcnt lgkmcnt(7)
	v_mfma_f32_16x16x32_bf16 v[54:57], v[224:227], v[138:141], 0
	ds_read_b128 v[224:227], v169 offset:57600
	s_waitcnt lgkmcnt(7)
	v_mfma_f32_16x16x32_bf16 v[54:57], v[228:231], v[134:137], v[54:57]
	ds_read_b128 v[228:231], v169 offset:58112
	s_waitcnt lgkmcnt(7)
	v_mfma_f32_16x16x32_bf16 v[54:57], v[232:235], v[130:133], v[54:57]
	ds_read_b128 v[232:235], v169 offset:58624
	s_waitcnt lgkmcnt(7)
	v_mfma_f32_16x16x32_bf16 v[58:61], v[246:249], v[62:65], v[54:57]
	ds_read_b128 v[246:249], v169 offset:59136
	s_waitcnt lgkmcnt(7)
	v_mfma_f32_16x16x32_bf16 v[54:57], v[208:211], v[138:141], 0
	s_waitcnt lgkmcnt(6)
	v_mfma_f32_16x16x32_bf16 v[54:57], v[212:215], v[134:137], v[54:57]
	s_waitcnt lgkmcnt(5)
	v_mfma_f32_16x16x32_bf16 v[54:57], v[216:219], v[130:133], v[54:57]
	s_waitcnt lgkmcnt(4)
	v_mfma_f32_16x16x32_bf16 v[54:57], v[220:223], v[62:65], v[54:57]
	s_waitcnt lgkmcnt(3)
	v_mfma_f32_16x16x32_bf16 v[138:141], v[224:227], v[138:141], 0
	s_waitcnt lgkmcnt(2)
	v_mfma_f32_16x16x32_bf16 v[134:137], v[228:231], v[134:137], v[138:141]
	s_waitcnt lgkmcnt(1)
	v_mfma_f32_16x16x32_bf16 v[130:133], v[232:235], v[130:133], v[134:137]
	s_waitcnt lgkmcnt(0)
	v_mfma_f32_16x16x32_bf16 v[62:65], v[246:249], v[62:65], v[130:133]
	s_nop 7
	s_nop 2
	v_mul_lo_u32 v130, v195, s4
	v_add_u32_e32 v130, 0, v130
	v_add_u32_e32 v135, 0x20400, v130
	v_mov_b32_e32 v132, 0xff800000
	v_lshl_add_u32 v130, v170, 2, v135
	v_mov_b32_e32 v133, 0xff800000
	s_and_saveexec_b64 s[34:35], s[36:37]
	s_cbranch_execz .LBB9_676
	ds_read_b32 v131, v130 offset:928
	s_waitcnt lgkmcnt(0)
	v_add_f32_e32 v133, v126, v131

; #define LAS __attribute__((address_space(3)))
; #define ATT_KLOAD(buf, p) do { const bf16_t* kp_ = kloc + (size_t)((p) * 8 * NH) * 1024; \
;         _Pragma("unroll") for (int f = 0; f < 2; ++f) _Pragma("unroll") for (int ks = 0; ks < 4; ++ks) ka[buf][f * 4 + ks] = *(const bf16x8*)(kp_ + f * 128 + ks * 256); } while (0)
; template <bool LOCAL>
; __device__ __forceinline__ void attn_unit(const bf16_t* Q, const bf16_t* KT, const bf16_t* VT, bf16_t* O, LAS unsigned char* lds, int b, int h, int r, int w, int tq, int lane) {
;     const int g = lane >> 4, q = lane & 15;
;     const int qrow = LOCAL ? (b * SEQ + r * GRID_W + 16 * w + q) : (ML + b * CTX + 16 * tq + q);
;     bf16x8 bq[4];
;     { const bf16_t* qp = Q + (size_t)qrow * D + h * HD + 8 * g;
; #pragma unroll
;       for (int ks = 0; ks < 4; ++ks) bq[ks] = *(const bf16x8*)(qp + 32 * ks); }
;     constexpr int NP = LOCAL ? 16 : 8, CP = LOCAL ? 8 : 0;
;     f32x4 s[2 * NP];
;     int rs = 0, ws = 0;
;     if (LOCAL) { rs = r - 4; rs = rs < 0 ? 0 : (rs > 24 ? 24 : rs); ws = 16 * w - 8; ws = ws < 0 ? 0 : (ws > 32 ? 32 : ws); }
;     const int rgl = b * SEQ + rs * GRID_W + ws;
;     if (LOCAL) {
;         const bf16_t* kloc = KT + ((size_t)(((rgl >> 3) + (q >> 2)) * NH + h)) * 1024 + (q & 3) * 32 + g * 8;
;         bf16x8 ka[2][8];
;     ...
;         ATT_KLOAD(0, 0);
; #pragma unroll
;         for (int p = 0; p < 8; ++p) {
;             __builtin_amdgcn_s_barrier();
;             if (p + 1 < 8) ATT_KLOAD((p + 1) & 1, p + 1);
;             __builtin_amdgcn_sched_barrier(0);
; #pragma unroll
;             for (int f = 0; f < 2; ++f) { f32x4 a = {0.f, 0.f, 0.f, 0.f};
; #pragma unroll
;                 for (int ks = 0; ks < 4; ++ks) a = __builtin_amdgcn_mfma_f32_16x16x32_bf16(ka[p & 1][f * 4 + ks], bq[ks], a, 0, 0, 0);
;                 s[2 * p + f] = a; }
;             __builtin_amdgcn_sched_barrier(0);
;         }
;     ...
;     }
;     {
;         const LAS unsigned char* kl = lds + (q >> 2) * 2048 + (((q & 3) * 4 + g) ^ ((q >> 2) & 2)) * 16;
; #pragma unroll
;         for (int p = 0; p < 8; ++p)
; #pragma unroll
;             for (int f = 0; f < 2; ++f) { f32x4 a = {0.f, 0.f, 0.f, 0.f};
; #pragma unroll
;                 for (int ks = 0; ks < 4; ++ks) a = __builtin_amdgcn_mfma_f32_16x16x32_bf16(*(const LAS bf16x8*)(kl + p * 8192 + ks * 512 + f * 256), bq[ks], a, 0, 0, 0);
;                 s[2 * (CP + p) + f] = a; }
;     }
.LBB9_802:
	s_and_b64 vcc, exec, s[24:25]
	s_cbranch_vccz .LBB9_658
	s_and_b32 s4, s70, 3
	s_lshl_b32 s4, s4, 6
	s_add_i32 s71, s71, s4
	v_add_u32_e32 v2, s71, v179
	v_ashrrev_i32_e32 v3, 31, v2
	v_lshlrev_b64 v[78:79], 12, v[2:3]
	v_lshl_add_u64 v[2:3], s[96:97], 0, v[78:79]
	s_lshl_b32 s48, s33, 1
	v_lshl_add_u64 v[2:3], v[2:3], 0, s[48:49]
	v_lshl_add_u64 v[2:3], v[2:3], 0, v[186:187]
	global_load_dwordx4 v[42:45], v[2:3], off
	global_load_dwordx4 v[38:41], v[2:3], off offset:64
	global_load_dwordx4 v[34:37], v[2:3], off offset:128
	global_load_dwordx4 v[30:33], v[2:3], off offset:192
	s_waitcnt lgkmcnt(0)
	v_mov_b32_e32 v157, v187
	ds_read_b128 v[208:211], v180
	ds_read_b128 v[212:215], v180 offset:512
	ds_read_b128 v[216:219], v180 offset:1024
	ds_read_b128 v[220:223], v180 offset:1536
	ds_read_b128 v[224:227], v180 offset:256
	ds_read_b128 v[228:231], v180 offset:768
	ds_read_b128 v[232:235], v180 offset:1280
	ds_read_b128 v[246:249], v180 offset:1792
	s_waitcnt vmcnt(3) lgkmcnt(7)
	v_mfma_f32_16x16x32_bf16 v[2:5], v[208:211], v[42:45], 0
	ds_read_b128 v[208:211], v180 offset:8192
	s_waitcnt vmcnt(2) lgkmcnt(7)
	v_mfma_f32_16x16x32_bf16 v[2:5], v[212:215], v[38:41], v[2:5]
	ds_read_b128 v[212:215], v180 offset:8704
	s_waitcnt vmcnt(1) lgkmcnt(7)
	v_mfma_f32_16x16x32_bf16 v[2:5], v[216:219], v[34:37], v[2:5]
	ds_read_b128 v[216:219], v180 offset:9216
	s_waitcnt vmcnt(0) lgkmcnt(7)
	v_mfma_f32_16x16x32_bf16 v[2:5], v[220:223], v[30:33], v[2:5]
	ds_read_b128 v[220:223], v180 offset:9728
	s_waitcnt lgkmcnt(7)
	v_mfma_f32_16x16x32_bf16 v[6:9], v[224:227], v[42:45], 0
	ds_read_b128 v[224:227], v180 offset:8448
	s_waitcnt lgkmcnt(7)
	v_mfma_f32_16x16x32_bf16 v[6:9], v[228:231], v[38:41], v[6:9]
	ds_read_b128 v[228:231], v180 offset:8960
	s_waitcnt lgkmcnt(7)
	v_mfma_f32_16x16x32_bf16 v[6:9], v[232:235], v[34:37], v[6:9]
	ds_read_b128 v[232:235], v180 offset:9472
	s_waitcnt lgkmcnt(7)
	v_mfma_f32_16x16x32_bf16 v[6:9], v[246:249], v[30:33], v[6:9]
	ds_read_b128 v[246:249], v180 offset:9984
	s_waitcnt lgkmcnt(7)
	v_mfma_f32_16x16x32_bf16 v[10:13], v[208:211], v[42:45], 0
	ds_read_b128 v[208:211], v180 offset:16384
	s_waitcnt lgkmcnt(7)
	v_mfma_f32_16x16x32_bf16 v[10:13], v[212:215], v[38:41], v[10:13]
	ds_read_b128 v[212:215], v180 offset:16896
	s_waitcnt lgkmcnt(7)
	v_mfma_f32_16x16x32_bf16 v[10:13], v[216:219], v[34:37], v[10:13]
	ds_read_b128 v[216:219], v180 offset:17408
	s_waitcnt lgkmcnt(7)
	v_mfma_f32_16x16x32_bf16 v[10:13], v[220:223], v[30:33], v[10:13]
	ds_read_b128 v[220:223], v180 offset:17920
	s_waitcnt lgkmcnt(7)
	v_mfma_f32_16x16x32_bf16 v[14:17], v[224:227], v[42:45], 0
	ds_read_b128 v[224:227], v180 offset:16640
	s_waitcnt lgkmcnt(7)
	v_mfma_f32_16x16x32_bf16 v[14:17], v[228:231], v[38:41], v[14:17]
	ds_read_b128 v[228:231], v180 offset:17152
	s_waitcnt lgkmcnt(7)
	v_mfma_f32_16x16x32_bf16 v[14:17], v[232:235], v[34:37], v[14:17]
	ds_read_b128 v[232:235], v180 offset:17664
	s_waitcnt lgkmcnt(7)
	v_mfma_f32_16x16x32_bf16 v[14:17], v[246:249], v[30:33], v[14:17]
	ds_read_b128 v[246:249], v180 offset:18176
	s_waitcnt lgkmcnt(7)
	v_mfma_f32_16x16x32_bf16 v[18:21], v[208:211], v[42:45], 0
	ds_read_b128 v[208:211], v180 offset:24576
	s_waitcnt lgkmcnt(7)
	v_mfma_f32_16x16x32_bf16 v[18:21], v[212:215], v[38:41], v[18:21]
	ds_read_b128 v[212:215], v180 offset:25088
	s_waitcnt lgkmcnt(7)
	v_mfma_f32_16x16x32_bf16 v[18:21], v[216:219], v[34:37], v[18:21]
	ds_read_b128 v[216:219], v180 offset:25600
	s_waitcnt lgkmcnt(7)
	v_mfma_f32_16x16x32_bf16 v[18:21], v[220:223], v[30:33], v[18:21]
	ds_read_b128 v[220:223], v180 offset:26112
	s_waitcnt lgkmcnt(7)
	v_mfma_f32_16x16x32_bf16 v[22:25], v[224:227], v[42:45], 0
	ds_read_b128 v[224:227], v180 offset:24832
	s_waitcnt lgkmcnt(7)
	v_mfma_f32_16x16x32_bf16 v[22:25], v[228:231], v[38:41], v[22:25]
	ds_read_b128 v[228:231], v180 offset:25344
	s_waitcnt lgkmcnt(7)
	v_mfma_f32_16x16x32_bf16 v[22:25], v[232:235], v[34:37], v[22:25]
	ds_read_b128 v[232:235], v180 offset:25856
	s_waitcnt lgkmcnt(7)
	v_mfma_f32_16x16x32_bf16 v[22:25], v[246:249], v[30:33], v[22:25]
	ds_read_b128 v[246:249], v180 offset:26368
	s_waitcnt lgkmcnt(7)
	v_mfma_f32_16x16x32_bf16 v[26:29], v[208:211], v[42:45], 0
	ds_read_b128 v[208:211], v180 offset:32768
	s_waitcnt lgkmcnt(7)
	v_mfma_f32_16x16x32_bf16 v[26:29], v[212:215], v[38:41], v[26:29]
	ds_read_b128 v[212:215], v180 offset:33280
	s_waitcnt lgkmcnt(7)
	v_mfma_f32_16x16x32_bf16 v[26:29], v[216:219], v[34:37], v[26:29]
	ds_read_b128 v[216:219], v180 offset:33792
	s_waitcnt lgkmcnt(7)
	v_mfma_f32_16x16x32_bf16 v[26:29], v[220:223], v[30:33], v[26:29]
	ds_read_b128 v[220:223], v180 offset:34304
	s_waitcnt lgkmcnt(7)
	v_mfma_f32_16x16x32_bf16 v[46:49], v[224:227], v[42:45], 0
	ds_read_b128 v[224:227], v180 offset:33024
	s_waitcnt lgkmcnt(7)
	v_mfma_f32_16x16x32_bf16 v[46:49], v[228:231], v[38:41], v[46:49]
	ds_read_b128 v[228:231], v180 offset:33536
	s_waitcnt lgkmcnt(7)
	v_mfma_f32_16x16x32_bf16 v[46:49], v[232:235], v[34:37], v[46:49]
	ds_read_b128 v[232:235], v180 offset:34048
	s_waitcnt lgkmcnt(7)
	v_mfma_f32_16x16x32_bf16 v[54:57], v[246:249], v[30:33], v[46:49]
	ds_read_b128 v[246:249], v180 offset:34560
	s_waitcnt lgkmcnt(7)
	v_mfma_f32_16x16x32_bf16 v[46:49], v[208:211], v[42:45], 0
	ds_read_b128 v[208:211], v180 offset:40960
	s_waitcnt lgkmcnt(7)
	v_mfma_f32_16x16x32_bf16 v[46:49], v[212:215], v[38:41], v[46:49]
	ds_read_b128 v[212:215], v180 offset:41472
	s_waitcnt lgkmcnt(7)
	v_mfma_f32_16x16x32_bf16 v[46:49], v[216:219], v[34:37], v[46:49]
	ds_read_b128 v[216:219], v180 offset:41984
	s_waitcnt lgkmcnt(7)
; #define LAS __attribute__((address_space(3)))
; template <bool LOCAL>
; __device__ __forceinline__ void attn_unit(const bf16_t* Q, const bf16_t* KT, const bf16_t* VT, bf16_t* O, LAS unsigned char* lds, int b, int h, int r, int w, int tq, int lane) {
;     ...
;     {
;         const LAS unsigned char* kl = lds + (q >> 2) * 2048 + (((q & 3) * 4 + g) ^ ((q >> 2) & 2)) * 16;
; #pragma unroll
;         for (int p = 0; p < 8; ++p)
; #pragma unroll
;             for (int f = 0; f < 2; ++f) { f32x4 a = {0.f, 0.f, 0.f, 0.f};
; #pragma unroll
;                 for (int ks = 0; ks < 4; ++ks) a = __builtin_amdgcn_mfma_f32_16x16x32_bf16(*(const LAS bf16x8*)(kl + p * 8192 + ks * 512 + f * 256), bq[ks], a, 0, 0, 0);
;                 s[2 * (CP + p) + f] = a; }
;     }
;     if (LOCAL) {
;         const int c = 16 * w + q; int cs = c - 8; cs = cs < 0 ? 0 : (cs > 48 ? 48 : cs);
;         const LAS float* rp = (const LAS float*)(lds + LDS_MISC + 1024);
; #pragma unroll
;         for (int p = 0; p < 8; ++p) { const int ro = (rs + p - r + 7) * 31;
; #pragma unroll
;             for (int f = 0; f < 2; ++f)
; #pragma unroll
;                 for (int j = 0; j < 4; ++j) { const int kc = ws + 8 * g + 4 * f + j; const bool valid = (kc >= cs) && (kc < cs + 16);
;                     int rel = kc - c + 15; rel = rel < 0 ? 0 : (rel > 30 ? 30 : rel);
;                     const float bias = rp[ro + rel];
;                     s[p * 2 + f][j] = valid ? s[p * 2 + f][j] + bias : -INFINITY; } }
;     }
;     float mx = -INFINITY;
; #pragma unroll
;     for (int i = 0; i < 2 * NP; ++i) mx = fmaxf(mx, fmaxf(fmaxf(s[i][0], s[i][1]), fmaxf(s[i][2], s[i][3])));
;     mx = fmaxf(mx, __shfl_xor(mx, 16)); mx = fmaxf(mx, __shfl_xor(mx, 32));
	v_mfma_f32_16x16x32_bf16 v[46:49], v[220:223], v[30:33], v[46:49]
	ds_read_b128 v[220:223], v180 offset:42496
	s_waitcnt lgkmcnt(7)
	v_mfma_f32_16x16x32_bf16 v[50:53], v[224:227], v[42:45], 0
	ds_read_b128 v[224:227], v180 offset:41216
	s_waitcnt lgkmcnt(7)
	v_mfma_f32_16x16x32_bf16 v[50:53], v[228:231], v[38:41], v[50:53]
	ds_read_b128 v[228:231], v180 offset:41728
	s_waitcnt lgkmcnt(7)
	v_mfma_f32_16x16x32_bf16 v[50:53], v[232:235], v[34:37], v[50:53]
	ds_read_b128 v[232:235], v180 offset:42240
	s_waitcnt lgkmcnt(7)
	v_mfma_f32_16x16x32_bf16 v[66:69], v[246:249], v[30:33], v[50:53]
	ds_read_b128 v[246:249], v180 offset:42752
	s_waitcnt lgkmcnt(7)
	v_mfma_f32_16x16x32_bf16 v[50:53], v[208:211], v[42:45], 0
	ds_read_b128 v[208:211], v180 offset:49152
	s_waitcnt lgkmcnt(7)
	v_mfma_f32_16x16x32_bf16 v[50:53], v[212:215], v[38:41], v[50:53]
	ds_read_b128 v[212:215], v180 offset:49664
	s_waitcnt lgkmcnt(7)
	v_mfma_f32_16x16x32_bf16 v[50:53], v[216:219], v[34:37], v[50:53]
	ds_read_b128 v[216:219], v180 offset:50176
	s_waitcnt lgkmcnt(7)
	v_mfma_f32_16x16x32_bf16 v[50:53], v[220:223], v[30:33], v[50:53]
	ds_read_b128 v[220:223], v180 offset:50688
	s_waitcnt lgkmcnt(7)
	v_mfma_f32_16x16x32_bf16 v[58:61], v[224:227], v[42:45], 0
	ds_read_b128 v[224:227], v180 offset:49408
	s_waitcnt lgkmcnt(7)
	v_mfma_f32_16x16x32_bf16 v[58:61], v[228:231], v[38:41], v[58:61]
	ds_read_b128 v[228:231], v180 offset:49920
	s_waitcnt lgkmcnt(7)
	v_mfma_f32_16x16x32_bf16 v[58:61], v[232:235], v[34:37], v[58:61]
	ds_read_b128 v[232:235], v180 offset:50432
	s_waitcnt lgkmcnt(7)
	v_mfma_f32_16x16x32_bf16 v[70:73], v[246:249], v[30:33], v[58:61]
	ds_read_b128 v[246:249], v180 offset:50944
	s_waitcnt lgkmcnt(7)
	v_mfma_f32_16x16x32_bf16 v[58:61], v[208:211], v[42:45], 0
	ds_read_b128 v[208:211], v180 offset:57344
	s_waitcnt lgkmcnt(7)
	v_mfma_f32_16x16x32_bf16 v[58:61], v[212:215], v[38:41], v[58:61]
	ds_read_b128 v[212:215], v180 offset:57856
	s_waitcnt lgkmcnt(7)
	v_mfma_f32_16x16x32_bf16 v[58:61], v[216:219], v[34:37], v[58:61]
	ds_read_b128 v[216:219], v180 offset:58368
	s_waitcnt lgkmcnt(7)
	v_mfma_f32_16x16x32_bf16 v[58:61], v[220:223], v[30:33], v[58:61]
	ds_read_b128 v[220:223], v180 offset:58880
	s_waitcnt lgkmcnt(7)
	v_mfma_f32_16x16x32_bf16 v[62:65], v[224:227], v[42:45], 0
	ds_read_b128 v[224:227], v180 offset:57600
	s_waitcnt lgkmcnt(7)
	v_mfma_f32_16x16x32_bf16 v[62:65], v[228:231], v[38:41], v[62:65]
	ds_read_b128 v[228:231], v180 offset:58112
	s_waitcnt lgkmcnt(7)
	v_mfma_f32_16x16x32_bf16 v[62:65], v[232:235], v[34:37], v[62:65]
	ds_read_b128 v[232:235], v180 offset:58624
	s_waitcnt lgkmcnt(7)
	v_mfma_f32_16x16x32_bf16 v[74:77], v[246:249], v[30:33], v[62:65]
	ds_read_b128 v[246:249], v180 offset:59136
	s_waitcnt lgkmcnt(7)
	v_mfma_f32_16x16x32_bf16 v[62:65], v[208:211], v[42:45], 0
	s_waitcnt lgkmcnt(6)
	v_mfma_f32_16x16x32_bf16 v[62:65], v[212:215], v[38:41], v[62:65]
	s_waitcnt lgkmcnt(5)
	v_mfma_f32_16x16x32_bf16 v[62:65], v[216:219], v[34:37], v[62:65]
	s_waitcnt lgkmcnt(4)
	v_mfma_f32_16x16x32_bf16 v[62:65], v[220:223], v[30:33], v[62:65]
	s_waitcnt lgkmcnt(3)
	v_mfma_f32_16x16x32_bf16 v[42:45], v[224:227], v[42:45], 0
	s_waitcnt lgkmcnt(2)
	v_mfma_f32_16x16x32_bf16 v[38:41], v[228:231], v[38:41], v[42:45]
	s_waitcnt lgkmcnt(1)
	v_mfma_f32_16x16x32_bf16 v[34:37], v[232:235], v[34:37], v[38:41]
	s_waitcnt lgkmcnt(0)
	v_mfma_f32_16x16x32_bf16 v[30:33], v[246:249], v[30:33], v[34:37]
	s_nop 7
	s_nop 2
	v_max_f32_e32 v34, v5, v5
	v_max_f32_e32 v35, v4, v4
	v_max_f32_e32 v34, v35, v34
	v_max_f32_e32 v35, v9, v9
	v_max_f32_e32 v36, v8, v8
	v_max_f32_e32 v35, v36, v35
	v_max3_f32 v34, v2, v3, v34
	v_max3_f32 v35, v6, v7, v35
	v_max3_f32 v34, v34, s16, v35
	v_max_f32_e32 v35, v13, v13
	v_max_f32_e32 v36, v12, v12
	v_max_f32_e32 v35, v36, v35
	v_max_f32_e32 v36, v17, v17
	v_max_f32_e32 v37, v16, v16
	v_max_f32_e32 v36, v37, v36
	v_max3_f32 v35, v10, v11, v35
	v_max3_f32 v36, v14, v15, v36
	v_max3_f32 v34, v34, v35, v36
	v_max_f32_e32 v35, v21, v21
	v_max_f32_e32 v36, v20, v20
	v_max_f32_e32 v35, v36, v35
	v_max_f32_e32 v36, v25, v25
	v_max_f32_e32 v37, v24, v24
	v_max_f32_e32 v36, v37, v36
	v_max3_f32 v35, v18, v19, v35
	v_max3_f32 v36, v22, v23, v36
	v_max3_f32 v34, v34, v35, v36
	v_max_f32_e32 v35, v29, v29
	v_max_f32_e32 v36, v28, v28
	v_max_f32_e32 v35, v36, v35
	v_max_f32_e32 v36, v57, v57
	v_max_f32_e32 v37, v56, v56
	v_max_f32_e32 v36, v37, v36
	v_max3_f32 v35, v26, v27, v35
	v_max3_f32 v36, v54, v55, v36
	v_max3_f32 v34, v34, v35, v36
	v_max_f32_e32 v35, v49, v49
	v_max_f32_e32 v36, v48, v48
	v_max_f32_e32 v35, v36, v35
	v_max_f32_e32 v36, v69, v69
	v_max_f32_e32 v37, v68, v68
	v_max_f32_e32 v36, v37, v36
	v_max3_f32 v35, v46, v47, v35
	v_max3_f32 v36, v66, v67, v36
	v_max3_f32 v34, v34, v35, v36
	v_max_f32_e32 v35, v53, v53
	v_max_f32_e32 v36, v52, v52
	v_max_f32_e32 v35, v36, v35
	v_max_f32_e32 v36, v73, v73
	v_max_f32_e32 v37, v72, v72
	v_max_f32_e32 v36, v37, v36
	v_max3_f32 v35, v50, v51, v35
	v_max3_f32 v36, v70, v71, v36
	v_max3_f32 v34, v34, v35, v36
	v_max_f32_e32 v35, v61, v61
	v_max_f32_e32 v36, v60, v60
	v_max_f32_e32 v35, v36, v35
	v_max_f32_e32 v36, v77, v77
	v_max_f32_e32 v37, v76, v76
	v_max_f32_e32 v36, v37, v36
	v_max3_f32 v35, v58, v59, v35
	v_max3_f32 v36, v74, v75, v36
	v_max3_f32 v34, v34, v35, v36
	v_max_f32_e32 v35, v65, v65
	v_max_f32_e32 v36, v64, v64
	v_max_f32_e32 v35, v36, v35
	v_max_f32_e32 v36, v33, v33
	v_max_f32_e32 v37, v32, v32
	v_max_f32_e32 v36, v37, v36
	v_max3_f32 v35, v62, v63, v35
	v_max3_f32 v36, v30, v31, v36
	v_max3_f32 v34, v34, v35, v36
	ds_bpermute_b32 v35, v181, v34
	s_waitcnt lgkmcnt(0)
; __device__ __forceinline__ unsigned cvt_pk_bf16(float lo, float hi) { unsigned r; asm volatile("v_cvt_pk_bf16_f32 %0, %1, %2" : "=v"(r) : "v"(lo), "v"(hi)); return r; }
; __device__ __forceinline__ float fast_exp2(float x) { return __builtin_amdgcn_exp2f(x); }
; template <bool LOCAL>
; __device__ __forceinline__ void attn_unit(const bf16_t* Q, const bf16_t* KT, const bf16_t* VT, bf16_t* O, LAS unsigned char* lds, int b, int h, int r, int w, int tq, int lane) {
;     ...
;     float mx = -INFINITY;
; #pragma unroll
;     for (int i = 0; i < 2 * NP; ++i) mx = fmaxf(mx, fmaxf(fmaxf(s[i][0], s[i][1]), fmaxf(s[i][2], s[i][3])));
;     mx = fmaxf(mx, __shfl_xor(mx, 16)); mx = fmaxf(mx, __shfl_xor(mx, 32));
;     float sum = 0.f; const float mxl = mx * 1.4426950408889634f;
;     bf16x8 pb[NP];
; #pragma unroll
;     for (int p = 0; p < NP; ++p) { float e[8];
; #pragma unroll
;         for (int f = 0; f < 2; ++f)
; #pragma unroll
;             for (int j = 0; j < 4; ++j) { e[4 * f + j] = fast_exp2(fmaf(s[2 * p + f][j], 1.4426950408889634f, -mxl)); sum += e[4 * f + j]; }
;         u32x4 pw; pw.x = cvt_pk_bf16(e[0], e[1]); pw.y = cvt_pk_bf16(e[2], e[3]); pw.z = cvt_pk_bf16(e[4], e[5]); pw.w = cvt_pk_bf16(e[6], e[7]);
;         pb[p] = __builtin_bit_cast(bf16x8, pw); }
;     sum += __shfl_xor(sum, 16); sum += __shfl_xor(sum, 32);
	v_max_f32_e32 v35, v35, v35
	v_max_f32_e32 v34, v34, v35
	ds_bpermute_b32 v35, v182, v34
	s_waitcnt lgkmcnt(0)
	v_max_f32_e32 v35, v35, v35
	v_max_f32_e32 v34, v34, v35
	v_mul_f32_e32 v42, 0xbfb8aa3b, v34
	v_fmamk_f32 v2, v2, 0x3fb8aa3b, v42
	v_exp_f32_e32 v2, v2
	v_fmamk_f32 v3, v3, 0x3fb8aa3b, v42
	v_exp_f32_e32 v3, v3
	v_fmamk_f32 v4, v4, 0x3fb8aa3b, v42
	v_exp_f32_e32 v4, v4
	v_fmamk_f32 v5, v5, 0x3fb8aa3b, v42
	v_exp_f32_e32 v5, v5
	v_fmamk_f32 v6, v6, 0x3fb8aa3b, v42
	v_add_f32_e32 v34, 0, v2
	v_exp_f32_e32 v6, v6
	v_fmamk_f32 v7, v7, 0x3fb8aa3b, v42
	v_add_f32_e32 v34, v3, v34
	v_exp_f32_e32 v7, v7
	v_fmamk_f32 v8, v8, 0x3fb8aa3b, v42
	v_add_f32_e32 v34, v4, v34
	v_exp_f32_e32 v8, v8
	v_fmamk_f32 v9, v9, 0x3fb8aa3b, v42
	v_add_f32_e32 v34, v5, v34
	v_exp_f32_e32 v9, v9
	v_cvt_pk_bf16_f32 v38, v2, v3
	v_fmamk_f32 v2, v10, 0x3fb8aa3b, v42
	v_add_f32_e32 v34, v6, v34
	v_cvt_pk_bf16_f32 v39, v4, v5
	v_exp_f32_e32 v2, v2
	v_fmamk_f32 v4, v11, 0x3fb8aa3b, v42
	v_add_f32_e32 v34, v7, v34
	v_exp_f32_e32 v4, v4
	v_fmamk_f32 v5, v12, 0x3fb8aa3b, v42
	v_add_f32_e32 v34, v8, v34
	v_cvt_pk_bf16_f32 v40, v6, v7
	v_exp_f32_e32 v5, v5
	v_fmamk_f32 v6, v13, 0x3fb8aa3b, v42
	v_add_f32_e32 v34, v9, v34
	v_exp_f32_e32 v6, v6
	v_fmamk_f32 v7, v14, 0x3fb8aa3b, v42
	v_cvt_pk_bf16_f32 v41, v8, v9
	v_add_f32_e32 v3, v2, v34
	v_exp_f32_e32 v7, v7
	v_fmamk_f32 v8, v15, 0x3fb8aa3b, v42
	v_add_f32_e32 v3, v4, v3
	v_exp_f32_e32 v8, v8
	v_fmamk_f32 v9, v16, 0x3fb8aa3b, v42
	v_add_f32_e32 v3, v5, v3
	v_exp_f32_e32 v9, v9
	v_fmamk_f32 v10, v17, 0x3fb8aa3b, v42
	v_add_f32_e32 v3, v6, v3
	v_exp_f32_e32 v10, v10
	v_cvt_pk_bf16_f32 v34, v2, v4
	v_fmamk_f32 v2, v18, 0x3fb8aa3b, v42
	v_add_f32_e32 v3, v7, v3
	v_exp_f32_e32 v2, v2
	v_fmamk_f32 v4, v19, 0x3fb8aa3b, v42
	v_add_f32_e32 v3, v8, v3
	v_cvt_pk_bf16_f32 v35, v5, v6
	v_exp_f32_e32 v4, v4
	v_fmamk_f32 v5, v20, 0x3fb8aa3b, v42
	v_add_f32_e32 v3, v9, v3
	v_exp_f32_e32 v5, v5
	v_fmamk_f32 v6, v21, 0x3fb8aa3b, v42
	v_add_f32_e32 v3, v10, v3
	v_cvt_pk_bf16_f32 v36, v7, v8
	v_exp_f32_e32 v6, v6
	v_fmamk_f32 v7, v22, 0x3fb8aa3b, v42
	v_add_f32_e32 v3, v2, v3
	v_exp_f32_e32 v7, v7
	v_fmamk_f32 v8, v23, 0x3fb8aa3b, v42
	v_cvt_pk_bf16_f32 v37, v9, v10
	v_add_f32_e32 v3, v4, v3
	v_exp_f32_e32 v8, v8
	v_fmamk_f32 v9, v24, 0x3fb8aa3b, v42
	v_add_f32_e32 v3, v5, v3
	v_exp_f32_e32 v9, v9
	v_fmamk_f32 v10, v25, 0x3fb8aa3b, v42
	v_add_f32_e32 v3, v6, v3
	v_exp_f32_e32 v10, v10
	v_cvt_pk_bf16_f32 v22, v2, v4
	v_fmamk_f32 v2, v26, 0x3fb8aa3b, v42
	v_add_f32_e32 v3, v7, v3
	v_exp_f32_e32 v2, v2
	v_fmamk_f32 v4, v27, 0x3fb8aa3b, v42
	v_add_f32_e32 v3, v8, v3
	v_cvt_pk_bf16_f32 v23, v5, v6
	v_exp_f32_e32 v4, v4
	v_fmamk_f32 v5, v28, 0x3fb8aa3b, v42
	v_add_f32_e32 v3, v9, v3
	v_exp_f32_e32 v5, v5
	v_fmamk_f32 v6, v29, 0x3fb8aa3b, v42
	v_add_f32_e32 v3, v10, v3
	v_cvt_pk_bf16_f32 v24, v7, v8
	v_exp_f32_e32 v6, v6
	v_fmamk_f32 v7, v54, 0x3fb8aa3b, v42
	v_add_f32_e32 v3, v2, v3
	v_exp_f32_e32 v7, v7
	v_fmamk_f32 v8, v55, 0x3fb8aa3b, v42
	v_cvt_pk_bf16_f32 v25, v9, v10
	v_add_f32_e32 v3, v4, v3
	v_exp_f32_e32 v8, v8
	v_fmamk_f32 v9, v56, 0x3fb8aa3b, v42
	v_add_f32_e32 v3, v5, v3
	v_exp_f32_e32 v9, v9
	v_fmamk_f32 v10, v57, 0x3fb8aa3b, v42
	v_add_f32_e32 v3, v6, v3
	v_exp_f32_e32 v10, v10
	v_cvt_pk_bf16_f32 v18, v2, v4
	v_fmamk_f32 v2, v46, 0x3fb8aa3b, v42
	v_add_f32_e32 v3, v7, v3
	v_exp_f32_e32 v2, v2
	v_fmamk_f32 v4, v47, 0x3fb8aa3b, v42
	v_add_f32_e32 v3, v8, v3
	v_cvt_pk_bf16_f32 v19, v5, v6
	v_exp_f32_e32 v4, v4
	v_fmamk_f32 v5, v48, 0x3fb8aa3b, v42
	v_add_f32_e32 v3, v9, v3
	v_exp_f32_e32 v5, v5
	v_fmamk_f32 v6, v49, 0x3fb8aa3b, v42
	v_add_f32_e32 v3, v10, v3
	v_cvt_pk_bf16_f32 v20, v7, v8
	v_exp_f32_e32 v6, v6
	v_fmamk_f32 v7, v66, 0x3fb8aa3b, v42
	v_add_f32_e32 v3, v2, v3
	v_exp_f32_e32 v7, v7
	v_fmamk_f32 v8, v67, 0x3fb8aa3b, v42
	v_cvt_pk_bf16_f32 v21, v9, v10
	v_add_f32_e32 v3, v4, v3
	v_exp_f32_e32 v8, v8
	v_fmamk_f32 v9, v68, 0x3fb8aa3b, v42
	v_add_f32_e32 v3, v5, v3
	v_exp_f32_e32 v9, v9
	v_fmamk_f32 v10, v69, 0x3fb8aa3b, v42
	v_add_f32_e32 v3, v6, v3
	v_exp_f32_e32 v10, v10
	v_cvt_pk_bf16_f32 v14, v2, v4
	v_fmamk_f32 v2, v50, 0x3fb8aa3b, v42
	v_add_f32_e32 v3, v7, v3
	v_exp_f32_e32 v2, v2
	v_fmamk_f32 v4, v51, 0x3fb8aa3b, v42
	v_add_f32_e32 v3, v8, v3
	v_cvt_pk_bf16_f32 v15, v5, v6
	v_exp_f32_e32 v4, v4
	v_fmamk_f32 v5, v52, 0x3fb8aa3b, v42
	v_add_f32_e32 v3, v9, v3
	v_exp_f32_e32 v5, v5
	v_fmamk_f32 v6, v53, 0x3fb8aa3b, v42
	v_add_f32_e32 v3, v10, v3
	v_cvt_pk_bf16_f32 v16, v7, v8
	v_exp_f32_e32 v6, v6
	v_fmamk_f32 v7, v70, 0x3fb8aa3b, v42
	v_add_f32_e32 v3, v2, v3
	v_exp_f32_e32 v7, v7
	v_fmamk_f32 v8, v71, 0x3fb8aa3b, v42
	v_cvt_pk_bf16_f32 v17, v9, v10
	v_add_f32_e32 v3, v4, v3
	v_exp_f32_e32 v8, v8
	v_fmamk_f32 v9, v72, 0x3fb8aa3b, v42
	v_add_f32_e32 v3, v5, v3
	v_exp_f32_e32 v9, v9
	v_fmamk_f32 v10, v73, 0x3fb8aa3b, v42
	v_add_f32_e32 v3, v6, v3
	v_exp_f32_e32 v13, v10
	v_cvt_pk_bf16_f32 v10, v2, v4
	v_fmamk_f32 v2, v58, 0x3fb8aa3b, v42
	v_add_f32_e32 v3, v7, v3
	v_exp_f32_e32 v2, v2
	v_fmamk_f32 v4, v59, 0x3fb8aa3b, v42
	v_add_f32_e32 v3, v8, v3
	v_cvt_pk_bf16_f32 v11, v5, v6
	v_exp_f32_e32 v4, v4
	v_fmamk_f32 v5, v60, 0x3fb8aa3b, v42
	v_add_f32_e32 v3, v9, v3
	v_exp_f32_e32 v5, v5
	v_fmamk_f32 v6, v61, 0x3fb8aa3b, v42
	v_add_f32_e32 v3, v13, v3
	v_cvt_pk_bf16_f32 v12, v7, v8
	v_exp_f32_e32 v7, v6
	v_fmamk_f32 v6, v74, 0x3fb8aa3b, v42
	v_add_f32_e32 v3, v2, v3
	v_exp_f32_e32 v8, v6
	v_fmamk_f32 v6, v75, 0x3fb8aa3b, v42
	v_cvt_pk_bf16_f32 v13, v9, v13
	v_add_f32_e32 v3, v4, v3
	v_exp_f32_e32 v9, v6
	v_fmamk_f32 v6, v76, 0x3fb8aa3b, v42
	v_add_f32_e32 v3, v5, v3
	v_exp_f32_e32 v26, v6
	v_fmamk_f32 v6, v77, 0x3fb8aa3b, v42
	v_add_f32_e32 v3, v7, v3
	v_exp_f32_e32 v27, v6
	v_cvt_pk_bf16_f32 v6, v2, v4
	v_fmamk_f32 v2, v62, 0x3fb8aa3b, v42
	v_add_f32_e32 v3, v8, v3
	v_exp_f32_e32 v2, v2
	v_fmamk_f32 v4, v63, 0x3fb8aa3b, v42
	v_add_f32_e32 v3, v9, v3
	v_cvt_pk_bf16_f32 v7, v5, v7
	v_exp_f32_e32 v4, v4
	v_fmamk_f32 v5, v64, 0x3fb8aa3b, v42
	v_add_f32_e32 v3, v26, v3
	v_cvt_pk_bf16_f32 v8, v8, v9
	v_cvt_pk_bf16_f32 v9, v26, v27
	v_exp_f32_e32 v5, v5
	v_fmamk_f32 v26, v65, 0x3fb8aa3b, v42
	v_add_f32_e32 v3, v27, v3
	v_exp_f32_e32 v26, v26
	v_fmamk_f32 v27, v30, 0x3fb8aa3b, v42
	v_add_f32_e32 v3, v2, v3
	v_exp_f32_e32 v27, v27
	v_fmamk_f32 v28, v31, 0x3fb8aa3b, v42
	v_add_f32_e32 v3, v4, v3
	v_exp_f32_e32 v28, v28
	v_fmamk_f32 v29, v32, 0x3fb8aa3b, v42
	v_add_f32_e32 v3, v5, v3
	v_exp_f32_e32 v29, v29
	v_fmac_f32_e32 v42, 0x3fb8aa3b, v33
	v_add_f32_e32 v3, v26, v3
	v_exp_f32_e32 v30, v42
	v_add_f32_e32 v3, v27, v3
	v_add_f32_e32 v3, v28, v3
	v_add_f32_e32 v3, v29, v3
	v_add_f32_e32 v31, v30, v3
	v_cvt_pk_bf16_f32 v2, v2, v4
	v_cvt_pk_bf16_f32 v3, v5, v26
	ds_bpermute_b32 v26, v181, v31
	v_cvt_pk_bf16_f32 v4, v27, v28
	v_cvt_pk_bf16_f32 v5, v29, v30
	s_waitcnt lgkmcnt(0)
; #define LAS __attribute__((address_space(3)))
; #define ATT_VLOAD(buf, p) do { const bf16_t* vp_ = vloc + (size_t)((p) * 8 * NH) * 1024; \
;         _Pragma("unroll") for (int df = 0; df < 8; ++df) va[buf][df] = *(const bf16x8*)(vp_ + df * 128); } while (0)
; template <bool LOCAL>
; __device__ __forceinline__ void attn_unit(const bf16_t* Q, const bf16_t* KT, const bf16_t* VT, bf16_t* O, LAS unsigned char* lds, int b, int h, int r, int w, int tq, int lane) {
;     ...
;     sum += __shfl_xor(sum, 16); sum += __shfl_xor(sum, 32);
;     f32x4 o[8];
; #pragma unroll
;     for (int df = 0; df < 8; ++df) o[df] = (f32x4){0.f, 0.f, 0.f, 0.f};
;     if (LOCAL) {
;         const bf16_t* vloc = VT + ((size_t)(((rgl >> 3) + g) * NH + h)) * 1024 + q * 8;
;         bf16x8 va[2][8];
;     ...
;         ATT_VLOAD(0, 0);
; #pragma unroll
;         for (int p = 0; p < 8; ++p) {
;             __builtin_amdgcn_s_barrier();
;             if (p + 1 < 8) ATT_VLOAD((p + 1) & 1, p + 1);
;             __builtin_amdgcn_sched_barrier(0);
; #pragma unroll
;             for (int df = 0; df < 8; ++df) o[df] = __builtin_amdgcn_mfma_f32_16x16x32_bf16(va[p & 1][df], pb[p], o[df], 0, 0, 0);
;             __builtin_amdgcn_sched_barrier(0);
;         }
;     ...
;     }
;     {
;         const LAS unsigned char* vl = lds + 65536 + g * 2048 + q * 16;
; #pragma unroll
;         for (int p = 0; p < 8; ++p)
; #pragma unroll
;             for (int df = 0; df < 8; ++df) o[df] = __builtin_amdgcn_mfma_f32_16x16x32_bf16(*(const LAS bf16x8*)(vl + p * 8192 + df * 256), pb[CP + p], o[df], 0, 0, 0);
;     }
	v_add_f32_e32 v26, v31, v26
	ds_bpermute_b32 v27, v182, v26
	ds_read_b128 v[208:211], v178
	ds_read_b128 v[212:215], v178 offset:256
	ds_read_b128 v[216:219], v178 offset:512
	ds_read_b128 v[220:223], v178 offset:768
	ds_read_b128 v[224:227], v178 offset:1024
	ds_read_b128 v[228:231], v178 offset:1280
	ds_read_b128 v[232:235], v178 offset:1536
	ds_read_b128 v[246:249], v178 offset:1792
	s_waitcnt lgkmcnt(7)
	v_mfma_f32_16x16x32_bf16 v[28:31], v[208:211], v[38:41], 0
	ds_read_b128 v[208:211], v178 offset:8192
	s_waitcnt lgkmcnt(7)
	v_mfma_f32_16x16x32_bf16 v[42:45], v[212:215], v[38:41], 0
	ds_read_b128 v[212:215], v178 offset:8448
	s_waitcnt lgkmcnt(7)
	v_mfma_f32_16x16x32_bf16 v[46:49], v[216:219], v[38:41], 0
	ds_read_b128 v[216:219], v178 offset:8704
	s_waitcnt lgkmcnt(7)
	v_mfma_f32_16x16x32_bf16 v[50:53], v[220:223], v[38:41], 0
	ds_read_b128 v[220:223], v178 offset:8960
	s_waitcnt lgkmcnt(7)
	v_mfma_f32_16x16x32_bf16 v[54:57], v[224:227], v[38:41], 0
	ds_read_b128 v[224:227], v178 offset:9216
	s_waitcnt lgkmcnt(7)
	v_mfma_f32_16x16x32_bf16 v[58:61], v[228:231], v[38:41], 0
	ds_read_b128 v[228:231], v178 offset:9472
	s_waitcnt lgkmcnt(7)
	v_mfma_f32_16x16x32_bf16 v[62:65], v[232:235], v[38:41], 0
	ds_read_b128 v[232:235], v178 offset:9728
	s_waitcnt lgkmcnt(7)
	v_mfma_f32_16x16x32_bf16 v[38:41], v[246:249], v[38:41], 0
	ds_read_b128 v[246:249], v178 offset:9984
	s_waitcnt lgkmcnt(7)
	v_mfma_f32_16x16x32_bf16 v[28:31], v[208:211], v[34:37], v[28:31]
	ds_read_b128 v[208:211], v178 offset:16384
	s_waitcnt lgkmcnt(7)
	v_mfma_f32_16x16x32_bf16 v[42:45], v[212:215], v[34:37], v[42:45]
	ds_read_b128 v[212:215], v178 offset:16640
	s_waitcnt lgkmcnt(7)
	v_mfma_f32_16x16x32_bf16 v[46:49], v[216:219], v[34:37], v[46:49]
	ds_read_b128 v[216:219], v178 offset:16896
	s_waitcnt lgkmcnt(7)
	v_mfma_f32_16x16x32_bf16 v[50:53], v[220:223], v[34:37], v[50:53]
	ds_read_b128 v[220:223], v178 offset:17152
	s_waitcnt lgkmcnt(7)
	v_mfma_f32_16x16x32_bf16 v[54:57], v[224:227], v[34:37], v[54:57]
	ds_read_b128 v[224:227], v178 offset:17408
	s_waitcnt lgkmcnt(7)
	v_mfma_f32_16x16x32_bf16 v[58:61], v[228:231], v[34:37], v[58:61]
	ds_read_b128 v[228:231], v178 offset:17664
	s_waitcnt lgkmcnt(7)
	v_mfma_f32_16x16x32_bf16 v[62:65], v[232:235], v[34:37], v[62:65]
	ds_read_b128 v[232:235], v178 offset:17920
	s_waitcnt lgkmcnt(7)
	v_mfma_f32_16x16x32_bf16 v[32:35], v[246:249], v[34:37], v[38:41]
	ds_read_b128 v[246:249], v178 offset:18176
	s_waitcnt lgkmcnt(7)
	v_mfma_f32_16x16x32_bf16 v[28:31], v[208:211], v[22:25], v[28:31]
	ds_read_b128 v[208:211], v178 offset:24576
	s_waitcnt lgkmcnt(7)
	v_mfma_f32_16x16x32_bf16 v[36:39], v[212:215], v[22:25], v[42:45]
	ds_read_b128 v[212:215], v178 offset:24832
	s_waitcnt lgkmcnt(7)
	v_mfma_f32_16x16x32_bf16 v[40:43], v[216:219], v[22:25], v[46:49]
	ds_read_b128 v[216:219], v178 offset:25088
	s_waitcnt lgkmcnt(7)
	v_mfma_f32_16x16x32_bf16 v[44:47], v[220:223], v[22:25], v[50:53]
	ds_read_b128 v[220:223], v178 offset:25344
	s_waitcnt lgkmcnt(7)
	v_mfma_f32_16x16x32_bf16 v[48:51], v[224:227], v[22:25], v[54:57]
	ds_read_b128 v[224:227], v178 offset:25600
	s_waitcnt lgkmcnt(7)
	v_mfma_f32_16x16x32_bf16 v[52:55], v[228:231], v[22:25], v[58:61]
	ds_read_b128 v[228:231], v178 offset:25856
	s_waitcnt lgkmcnt(7)
	v_mfma_f32_16x16x32_bf16 v[56:59], v[232:235], v[22:25], v[62:65]
	ds_read_b128 v[232:235], v178 offset:26112
	s_waitcnt lgkmcnt(7)
	v_mfma_f32_16x16x32_bf16 v[22:25], v[246:249], v[22:25], v[32:35]
	ds_read_b128 v[246:249], v178 offset:26368
	s_waitcnt lgkmcnt(7)
	v_mfma_f32_16x16x32_bf16 v[28:31], v[208:211], v[18:21], v[28:31]
	ds_read_b128 v[208:211], v178 offset:32768
	s_waitcnt lgkmcnt(7)
	v_mfma_f32_16x16x32_bf16 v[32:35], v[212:215], v[18:21], v[36:39]
	ds_read_b128 v[212:215], v178 offset:33024
	s_waitcnt lgkmcnt(7)
	v_mfma_f32_16x16x32_bf16 v[36:39], v[216:219], v[18:21], v[40:43]
	ds_read_b128 v[216:219], v178 offset:33280
	s_waitcnt lgkmcnt(7)
	v_mfma_f32_16x16x32_bf16 v[40:43], v[220:223], v[18:21], v[44:47]
	ds_read_b128 v[220:223], v178 offset:33536
	s_waitcnt lgkmcnt(7)
	v_mfma_f32_16x16x32_bf16 v[44:47], v[224:227], v[18:21], v[48:51]
	ds_read_b128 v[224:227], v178 offset:33792
	s_waitcnt lgkmcnt(7)
	v_mfma_f32_16x16x32_bf16 v[48:51], v[228:231], v[18:21], v[52:55]
	ds_read_b128 v[228:231], v178 offset:34048
	s_waitcnt lgkmcnt(7)
	v_mfma_f32_16x16x32_bf16 v[52:55], v[232:235], v[18:21], v[56:59]
	ds_read_b128 v[232:235], v178 offset:34304
	s_waitcnt lgkmcnt(7)
	v_mfma_f32_16x16x32_bf16 v[18:21], v[246:249], v[18:21], v[22:25]
	ds_read_b128 v[246:249], v178 offset:34560
	s_waitcnt lgkmcnt(7)
	v_mfma_f32_16x16x32_bf16 v[22:25], v[208:211], v[14:17], v[28:31]
	ds_read_b128 v[208:211], v178 offset:40960
	s_waitcnt lgkmcnt(7)
	v_mfma_f32_16x16x32_bf16 v[28:31], v[212:215], v[14:17], v[32:35]
	ds_read_b128 v[212:215], v178 offset:41216
	s_waitcnt lgkmcnt(7)
	v_mfma_f32_16x16x32_bf16 v[32:35], v[216:219], v[14:17], v[36:39]
	ds_read_b128 v[216:219], v178 offset:41472
	s_waitcnt lgkmcnt(7)
	v_mfma_f32_16x16x32_bf16 v[36:39], v[220:223], v[14:17], v[40:43]
	ds_read_b128 v[220:223], v178 offset:41728
	s_waitcnt lgkmcnt(7)
	v_mfma_f32_16x16x32_bf16 v[40:43], v[224:227], v[14:17], v[44:47]
	ds_read_b128 v[224:227], v178 offset:41984
	s_waitcnt lgkmcnt(7)
	v_mfma_f32_16x16x32_bf16 v[44:47], v[228:231], v[14:17], v[48:51]
	ds_read_b128 v[228:231], v178 offset:42240
	s_waitcnt lgkmcnt(7)
; #define LAS __attribute__((address_space(3)))
; __device__ __forceinline__ unsigned cvt_pk_bf16(float lo, float hi) { unsigned r; asm volatile("v_cvt_pk_bf16_f32 %0, %1, %2" : "=v"(r) : "v"(lo), "v"(hi)); return r; }
; template <bool LOCAL>
; __device__ __forceinline__ void attn_unit(const bf16_t* Q, const bf16_t* KT, const bf16_t* VT, bf16_t* O, LAS unsigned char* lds, int b, int h, int r, int w, int tq, int lane) {
;     ...
;     {
;         const LAS unsigned char* vl = lds + 65536 + g * 2048 + q * 16;
; #pragma unroll
;         for (int p = 0; p < 8; ++p)
; #pragma unroll
;             for (int df = 0; df < 8; ++df) o[df] = __builtin_amdgcn_mfma_f32_16x16x32_bf16(*(const LAS bf16x8*)(vl + p * 8192 + df * 256), pb[CP + p], o[df], 0, 0, 0);
;     }
;     const float inv = 1.f / sum;
;     bf16_t* op = O + (size_t)qrow * D + h * HD + 4 * g;
; #pragma unroll
;     for (int df = 0; df < 8; ++df) { u32x2 wv; wv.x = cvt_pk_bf16(o[df][0] * inv, o[df][1] * inv); wv.y = cvt_pk_bf16(o[df][2] * inv, o[df][3] * inv); *(u32x2*)(op + 16 * df) = wv; }
	v_mfma_f32_16x16x32_bf16 v[48:51], v[232:235], v[14:17], v[52:55]
	ds_read_b128 v[232:235], v178 offset:42496
	s_waitcnt lgkmcnt(7)
	v_mfma_f32_16x16x32_bf16 v[14:17], v[246:249], v[14:17], v[18:21]
	ds_read_b128 v[246:249], v178 offset:42752
	s_waitcnt lgkmcnt(7)
	v_mfma_f32_16x16x32_bf16 v[18:21], v[208:211], v[10:13], v[22:25]
	ds_read_b128 v[208:211], v178 offset:49152
	s_waitcnt lgkmcnt(7)
	v_mfma_f32_16x16x32_bf16 v[22:25], v[212:215], v[10:13], v[28:31]
	ds_read_b128 v[212:215], v178 offset:49408
	s_waitcnt lgkmcnt(7)
	v_mfma_f32_16x16x32_bf16 v[28:31], v[216:219], v[10:13], v[32:35]
	ds_read_b128 v[216:219], v178 offset:49664
	s_waitcnt lgkmcnt(7)
	v_mfma_f32_16x16x32_bf16 v[32:35], v[220:223], v[10:13], v[36:39]
	ds_read_b128 v[220:223], v178 offset:49920
	s_waitcnt lgkmcnt(7)
	v_mfma_f32_16x16x32_bf16 v[36:39], v[224:227], v[10:13], v[40:43]
	ds_read_b128 v[224:227], v178 offset:50176
	s_waitcnt lgkmcnt(7)
	v_mfma_f32_16x16x32_bf16 v[40:43], v[228:231], v[10:13], v[44:47]
	ds_read_b128 v[228:231], v178 offset:50432
	s_waitcnt lgkmcnt(7)
	v_mfma_f32_16x16x32_bf16 v[44:47], v[232:235], v[10:13], v[48:51]
	ds_read_b128 v[232:235], v178 offset:50688
	s_waitcnt lgkmcnt(7)
	v_mfma_f32_16x16x32_bf16 v[10:13], v[246:249], v[10:13], v[14:17]
	ds_read_b128 v[246:249], v178 offset:50944
	s_waitcnt lgkmcnt(7)
	v_mfma_f32_16x16x32_bf16 v[14:17], v[208:211], v[6:9], v[18:21]
	ds_read_b128 v[208:211], v178 offset:57344
	s_waitcnt lgkmcnt(7)
	v_mfma_f32_16x16x32_bf16 v[18:21], v[212:215], v[6:9], v[22:25]
	ds_read_b128 v[212:215], v178 offset:57600
	s_waitcnt lgkmcnt(7)
	v_mfma_f32_16x16x32_bf16 v[22:25], v[216:219], v[6:9], v[28:31]
	ds_read_b128 v[216:219], v178 offset:57856
	s_waitcnt lgkmcnt(7)
	v_mfma_f32_16x16x32_bf16 v[28:31], v[220:223], v[6:9], v[32:35]
	ds_read_b128 v[220:223], v178 offset:58112
	s_waitcnt lgkmcnt(7)
	v_mfma_f32_16x16x32_bf16 v[32:35], v[224:227], v[6:9], v[36:39]
	ds_read_b128 v[224:227], v178 offset:58368
	s_waitcnt lgkmcnt(7)
	v_mfma_f32_16x16x32_bf16 v[36:39], v[228:231], v[6:9], v[40:43]
	ds_read_b128 v[228:231], v178 offset:58624
	s_waitcnt lgkmcnt(7)
	v_mfma_f32_16x16x32_bf16 v[40:43], v[232:235], v[6:9], v[44:47]
	ds_read_b128 v[232:235], v178 offset:58880
	s_waitcnt lgkmcnt(7)
	v_mfma_f32_16x16x32_bf16 v[6:9], v[246:249], v[6:9], v[10:13]
	ds_read_b128 v[246:249], v178 offset:59136
	s_waitcnt lgkmcnt(7)
	v_mfma_f32_16x16x32_bf16 v[10:13], v[208:211], v[2:5], v[14:17]
	s_waitcnt lgkmcnt(6)
	v_mfma_f32_16x16x32_bf16 v[14:17], v[212:215], v[2:5], v[18:21]
	s_waitcnt lgkmcnt(5)
	v_mfma_f32_16x16x32_bf16 v[18:21], v[216:219], v[2:5], v[22:25]
	s_waitcnt lgkmcnt(4)
	v_mfma_f32_16x16x32_bf16 v[22:25], v[220:223], v[2:5], v[28:31]
	s_waitcnt lgkmcnt(3)
	v_mfma_f32_16x16x32_bf16 v[28:31], v[224:227], v[2:5], v[32:35]
	s_waitcnt lgkmcnt(2)
	v_mfma_f32_16x16x32_bf16 v[32:35], v[228:231], v[2:5], v[36:39]
	s_waitcnt lgkmcnt(1)
	v_mfma_f32_16x16x32_bf16 v[36:39], v[232:235], v[2:5], v[40:43]
	s_waitcnt lgkmcnt(0)
	v_mfma_f32_16x16x32_bf16 v[2:5], v[246:249], v[2:5], v[6:9]
	s_nop 7
	s_nop 2
	v_add_f32_e32 v6, v26, v27
	v_div_scale_f32 v7, s[4:5], v6, v6, 1.0
	v_rcp_f32_e32 v8, v7
	s_nop 0
	v_fma_f32 v9, -v7, v8, 1.0
	v_fmac_f32_e32 v8, v9, v8
	v_div_scale_f32 v9, vcc, 1.0, v6, 1.0
	v_mul_f32_e32 v26, v9, v8
	v_fma_f32 v27, -v7, v26, v9
	v_fmac_f32_e32 v26, v27, v8
	v_fma_f32 v7, -v7, v26, v9
	v_div_fmas_f32 v7, v7, v8, v26
	v_div_fixup_f32 v26, v7, v6, 1.0
	v_lshl_add_u64 v[6:7], s[92:93], 0, v[78:79]
	v_mul_f32_e32 v8, v26, v10
	v_mul_f32_e32 v9, v26, v11
	v_lshl_add_u64 v[6:7], v[6:7], 0, s[48:49]
	v_cvt_pk_bf16_f32 v8, v8, v9
	v_mul_f32_e32 v9, v26, v12
	v_lshl_add_u64 v[6:7], v[6:7], 0, v[156:157]
	v_mul_f32_e32 v10, v26, v13
	v_cvt_pk_bf16_f32 v9, v9, v10
	global_store_dwordx2 v[6:7], v[8:9], off
	v_mul_f32_e32 v8, v26, v14
	v_mul_f32_e32 v9, v26, v15
	v_cvt_pk_bf16_f32 v8, v8, v9
	v_mul_f32_e32 v9, v26, v16
	v_mul_f32_e32 v10, v26, v17
	v_cvt_pk_bf16_f32 v9, v9, v10
	global_store_dwordx2 v[6:7], v[8:9], off offset:32
	v_mul_f32_e32 v8, v26, v18
	v_mul_f32_e32 v9, v26, v19
	v_cvt_pk_bf16_f32 v8, v8, v9
	v_mul_f32_e32 v9, v26, v20
	v_mul_f32_e32 v10, v26, v21
	v_cvt_pk_bf16_f32 v9, v9, v10
	global_store_dwordx2 v[6:7], v[8:9], off offset:64
	v_mul_f32_e32 v8, v26, v22
	v_mul_f32_e32 v9, v26, v23
	v_cvt_pk_bf16_f32 v8, v8, v9
	v_mul_f32_e32 v9, v26, v24
	v_mul_f32_e32 v10, v26, v25
	v_cvt_pk_bf16_f32 v9, v9, v10
	global_store_dwordx2 v[6:7], v[8:9], off offset:96
	v_mul_f32_e32 v8, v26, v28
	v_mul_f32_e32 v9, v26, v29
	v_cvt_pk_bf16_f32 v8, v8, v9
	v_mul_f32_e32 v9, v26, v30
	v_mul_f32_e32 v10, v26, v31
	v_cvt_pk_bf16_f32 v9, v9, v10
	global_store_dwordx2 v[6:7], v[8:9], off offset:128
	v_mul_f32_e32 v8, v26, v32
	v_mul_f32_e32 v9, v26, v33
	v_cvt_pk_bf16_f32 v8, v8, v9
	v_mul_f32_e32 v9, v26, v34
	v_mul_f32_e32 v10, v26, v35
	v_cvt_pk_bf16_f32 v9, v9, v10
	global_store_dwordx2 v[6:7], v[8:9], off offset:160
	v_mul_f32_e32 v8, v26, v36
	v_mul_f32_e32 v9, v26, v37
	v_cvt_pk_bf16_f32 v8, v8, v9
	v_mul_f32_e32 v9, v26, v38
	v_mul_f32_e32 v2, v26, v2
	v_mul_f32_e32 v3, v26, v3
	v_mul_f32_e32 v10, v26, v39
	v_cvt_pk_bf16_f32 v9, v9, v10
	global_store_dwordx2 v[6:7], v[8:9], off offset:192
	v_cvt_pk_bf16_f32 v2, v2, v3
	v_mul_f32_e32 v3, v26, v4
	v_mul_f32_e32 v4, v26, v5
	v_cvt_pk_bf16_f32 v3, v3, v4
	global_store_dwordx2 v[6:7], v[2:3], off offset:224
	s_branch .LBB9_658
